# adds on v90: strategy 9 loop-edge edit - K-loop counter/pointer updates and exit compare moved in front of the iteration's last barrier (in-proj, fp8, out loops)
# baseline (speedup 1.0000x reference)
; #define PG8_STAGE(bufoff, gbase, voff) do { unsigned _g = (gbase); asm volatile("" : "+s"(_g));   _Pragma("unroll") for (int _i = 0; _i < 2; ++_i) \
;         __builtin_amdgcn_global_load_lds((const unsigned*)(wsb + (size_t)(unsigned)(_g + (voff)[_i])), (LAS unsigned*)(lds + (bufoff) + ldsw + _i * 8192), 16, 0, 0); } while (0)
; #define PG8_WAIT_V(n) asm volatile("s_waitcnt vmcnt(" #n ")" ::: "memory")
; #define PG8_WAIT_L(n) asm volatile("s_waitcnt lgkmcnt(" #n ")" ::: "memory")
; #define PG8_BAR __builtin_amdgcn_s_barrier()
; #define PG8_SCHED __builtin_amdgcn_sched_barrier(0)
;     ...
;             PG8_WAIT_V(8); PG8_WAIT_L(0); PG8_BAR; PG8_MMA(0, 0, At, B0); PG8_MMA(0, 1, At, B1); PG8_BAR; PG8_SCHED;
;             PG8_LDA(At, 1, 1); PG8_STAGE(PG8_SB(1, 0), b3, voffB); PG8_STAGE(PG8_SB(1, 1), b3 + hstep, voffB); PG8_STAGE(PG8_SA(1, 0), a3, voffA);
;             PG8_WAIT_V(8); PG8_WAIT_L(0); PG8_BAR; PG8_MMA(1, 0, At, B0); PG8_MMA(1, 1, At, B1); PG8_BAR; PG8_SCHED;
;     __device__ __forceinline__ void operator()(const f32x4 (&acc)[2][2][4][2], const pg8::GUnit& u, int wr, int wc, int fr, int fq) const {
;         bf16_t* base; int ldc, mode = 0, bjs = 128; int rowb = u.pm * 256 + wr * 64 + fr, colb = u.pn * 256 + wc * 32 + 8 * fq;
;         if (u.kind == 0) { base = P; ldc = INW; const int pn = u.pn; if (pn >= GA / 256) mode = 1; else if ((pn >= ZA / 256 && pn < QB / 256) || (pn >= ZB / 256 && pn < QM / 256) || (pn >= ZM / 256)) mode = 2;
.Lin_g2_join:
	s_waitcnt lgkmcnt(0)
	s_barrier
	s_waitcnt lgkmcnt(0)
	v_mfma_f32_16x16x32_bf16 v[126:129], v[138:141], v[178:181], v[126:129]
	v_mfma_f32_16x16x32_bf16 v[122:125], v[154:157], v[178:181], v[122:125]
	v_mfma_f32_16x16x32_bf16 v[110:113], v[138:141], v[186:189], v[110:113]
	v_mfma_f32_16x16x32_bf16 v[106:109], v[154:157], v[186:189], v[106:109]
	v_mfma_f32_16x16x32_bf16 v[94:97], v[138:141], v[194:197], v[94:97]
	v_mfma_f32_16x16x32_bf16 v[90:93], v[154:157], v[194:197], v[90:93]
	v_mfma_f32_16x16x32_bf16 v[78:81], v[138:141], v[202:205], v[78:81]
	v_mfma_f32_16x16x32_bf16 v[74:77], v[154:157], v[202:205], v[74:77]
	v_mfma_f32_16x16x32_bf16 v[126:129], v[142:145], v[182:185], v[126:129]
	v_mfma_f32_16x16x32_bf16 v[122:125], v[158:161], v[182:185], v[122:125]
	v_mfma_f32_16x16x32_bf16 v[110:113], v[142:145], v[190:193], v[110:113]
	v_mfma_f32_16x16x32_bf16 v[106:109], v[158:161], v[190:193], v[106:109]
	v_mfma_f32_16x16x32_bf16 v[94:97], v[142:145], v[198:201], v[94:97]
	v_mfma_f32_16x16x32_bf16 v[90:93], v[158:161], v[198:201], v[90:93]
	v_mfma_f32_16x16x32_bf16 v[78:81], v[142:145], v[206:209], v[78:81]
	v_mfma_f32_16x16x32_bf16 v[74:77], v[158:161], v[206:209], v[74:77]
	v_mfma_f32_16x16x32_bf16 v[118:121], v[162:165], v[178:181], v[118:121]
	v_mfma_f32_16x16x32_bf16 v[114:117], v[170:173], v[178:181], v[114:117]
	v_mfma_f32_16x16x32_bf16 v[102:105], v[162:165], v[186:189], v[102:105]
	v_mfma_f32_16x16x32_bf16 v[98:101], v[170:173], v[186:189], v[98:101]
	v_mfma_f32_16x16x32_bf16 v[86:89], v[162:165], v[194:197], v[86:89]
	v_mfma_f32_16x16x32_bf16 v[82:85], v[170:173], v[194:197], v[82:85]
	v_mfma_f32_16x16x32_bf16 v[70:73], v[162:165], v[202:205], v[70:73]
	v_mfma_f32_16x16x32_bf16 v[66:69], v[170:173], v[202:205], v[66:69]
	v_mfma_f32_16x16x32_bf16 v[118:121], v[166:169], v[182:185], v[118:121]
	v_mfma_f32_16x16x32_bf16 v[114:117], v[174:177], v[182:185], v[114:117]
	v_mfma_f32_16x16x32_bf16 v[102:105], v[166:169], v[190:193], v[102:105]
	v_mfma_f32_16x16x32_bf16 v[98:101], v[174:177], v[190:193], v[98:101]
	v_mfma_f32_16x16x32_bf16 v[86:89], v[166:169], v[198:201], v[86:89]
	v_mfma_f32_16x16x32_bf16 v[82:85], v[174:177], v[198:201], v[82:85]
	v_mfma_f32_16x16x32_bf16 v[70:73], v[166:169], v[206:209], v[70:73]
	v_mfma_f32_16x16x32_bf16 v[66:69], v[174:177], v[206:209], v[66:69]
	s_barrier
	s_add_i32 s83, s82, 0x80
	ds_read_b128 v[178:181], v153 offset:49152
	ds_read_b128 v[182:185], v153 offset:50176
	ds_read_b128 v[186:189], v153 offset:51200
	ds_read_b128 v[190:193], v153 offset:52224
	ds_read_b128 v[194:197], v153 offset:53248
	ds_read_b128 v[198:201], v153 offset:54272
	ds_read_b128 v[202:205], v153 offset:55296
	ds_read_b128 v[206:209], v153 offset:56320
	s_add_i32 s84, s84, s7
	s_add_i32 vcc_lo, s83, 0x10000000
	s_add_u32 vcc_lo, s100, vcc_lo
	s_addc_u32 vcc_hi, s101, 0
	s_mov_b32 m0, s84
	s_nop 0
	global_load_lds_dwordx4 v149, vcc
	s_add_i32 m0, s84, 0x2000
	s_add_i32 s82, s82, 0x100080
	global_load_lds_dwordx4 v151, vcc
	s_add_i32 s83, s96, s7
	s_add_i32 vcc_lo, s82, 0x10000000
	s_add_u32 vcc_lo, s100, vcc_lo
	s_addc_u32 vcc_hi, s101, 0
	s_mov_b32 m0, s83
	s_nop 0
	global_load_lds_dwordx4 v149, vcc
	s_add_i32 m0, s83, 0x2000
	s_nop 0
	global_load_lds_dwordx4 v151, vcc
	s_mov_b32 m0, s46
	s_add_i32 vcc_lo, s11, 0x10000000
	s_add_u32 vcc_lo, s100, vcc_lo
	s_addc_u32 vcc_hi, s101, 0
	global_load_lds_dwordx4 v148, vcc
	s_mov_b32 m0, s47
	s_nop 0
	global_load_lds_dwordx4 v150, vcc
	s_waitcnt vmcnt(8)
	s_waitcnt lgkmcnt(0)
	s_barrier
	s_waitcnt lgkmcnt(0)
	v_mfma_f32_16x16x32_bf16 v[62:65], v[138:141], v[178:181], v[62:65]
	v_mfma_f32_16x16x32_bf16 v[58:61], v[154:157], v[178:181], v[58:61]
	v_mfma_f32_16x16x32_bf16 v[46:49], v[138:141], v[186:189], v[46:49]
	v_mfma_f32_16x16x32_bf16 v[42:45], v[154:157], v[186:189], v[42:45]
	v_mfma_f32_16x16x32_bf16 v[30:33], v[138:141], v[194:197], v[30:33]
	v_mfma_f32_16x16x32_bf16 v[26:29], v[154:157], v[194:197], v[26:29]
	v_mfma_f32_16x16x32_bf16 v[14:17], v[138:141], v[202:205], v[14:17]
	v_mfma_f32_16x16x32_bf16 v[10:13], v[154:157], v[202:205], v[10:13]
	v_mfma_f32_16x16x32_bf16 v[62:65], v[142:145], v[182:185], v[62:65]
	v_mfma_f32_16x16x32_bf16 v[58:61], v[158:161], v[182:185], v[58:61]
	v_mfma_f32_16x16x32_bf16 v[46:49], v[142:145], v[190:193], v[46:49]
	v_mfma_f32_16x16x32_bf16 v[42:45], v[158:161], v[190:193], v[42:45]
	v_mfma_f32_16x16x32_bf16 v[30:33], v[142:145], v[198:201], v[30:33]
	v_mfma_f32_16x16x32_bf16 v[26:29], v[158:161], v[198:201], v[26:29]
	v_mfma_f32_16x16x32_bf16 v[14:17], v[142:145], v[206:209], v[14:17]
	v_mfma_f32_16x16x32_bf16 v[10:13], v[158:161], v[206:209], v[10:13]
	v_mfma_f32_16x16x32_bf16 v[54:57], v[162:165], v[178:181], v[54:57]
	v_mfma_f32_16x16x32_bf16 v[50:53], v[170:173], v[178:181], v[50:53]
	v_mfma_f32_16x16x32_bf16 v[38:41], v[162:165], v[186:189], v[38:41]
	v_mfma_f32_16x16x32_bf16 v[34:37], v[170:173], v[186:189], v[34:37]
	v_mfma_f32_16x16x32_bf16 v[22:25], v[162:165], v[194:197], v[22:25]
	v_mfma_f32_16x16x32_bf16 v[18:21], v[170:173], v[194:197], v[18:21]
	v_mfma_f32_16x16x32_bf16 v[6:9], v[162:165], v[202:205], v[6:9]
	v_mfma_f32_16x16x32_bf16 v[2:5], v[170:173], v[202:205], v[2:5]
	v_mfma_f32_16x16x32_bf16 v[54:57], v[166:169], v[182:185], v[54:57]
	v_mfma_f32_16x16x32_bf16 v[50:53], v[174:177], v[182:185], v[50:53]
	v_mfma_f32_16x16x32_bf16 v[38:41], v[166:169], v[190:193], v[38:41]
	v_mfma_f32_16x16x32_bf16 v[34:37], v[174:177], v[190:193], v[34:37]
	v_mfma_f32_16x16x32_bf16 v[22:25], v[166:169], v[198:201], v[22:25]
	v_mfma_f32_16x16x32_bf16 v[18:21], v[174:177], v[198:201], v[18:21]
	v_mfma_f32_16x16x32_bf16 v[6:9], v[166:169], v[206:209], v[6:9]
	v_mfma_f32_16x16x32_bf16 v[2:5], v[174:177], v[206:209], v[2:5]
	s_add_i32 s10, s10, 2
	s_addk_i32 s8, 0x100
	s_addk_i32 s9, 0x100
	s_cmp_gt_u32 s10, 61
	s_barrier
	s_cbranch_scc0 .LBB0_279
	s_setprio 0
	s_mov_b64 s[10:11], -1
	s_mov_b64 s[4:5], 0
	s_cmp_lt_i32 s18, 1
	s_mov_b64 s[8:9], 0
	v_mbcnt_lo_u32_b32 v0, -1, 0
	v_mbcnt_hi_u32_b32 v0, -1, v0
	s_cbranch_scc1 .LBB0_295
	s_cmp_lg_u32 s18, 1
	s_cselect_b64 s[8:9], -1, 0
	s_cbranch_execz .LBB0_296

; #define PG8_STAGE(bufoff, gbase, voff) do { unsigned _g = (gbase); asm volatile("" : "+s"(_g));   _Pragma("unroll") for (int _i = 0; _i < 2; ++_i) \
;         __builtin_amdgcn_global_load_lds((const unsigned*)(wsb + (size_t)(unsigned)(_g + (voff)[_i])), (LAS unsigned*)(lds + (bufoff) + ldsw + _i * 8192), 16, 0, 0); } while (0)
; #define PG8_WAIT_V(n) asm volatile("s_waitcnt vmcnt(" #n ")" ::: "memory")
; #define PG8_WAIT_L(n) asm volatile("s_waitcnt lgkmcnt(" #n ")" ::: "memory")
; #define PG8_BAR __builtin_amdgcn_s_barrier()
; #define PG8_SCHED __builtin_amdgcn_sched_barrier(0)
;     ...
;             PG8_LDB(B0, 0, 0); PG8_LDB(B1, 0, 1); PG8_SCHED; PG8_LDA(At, 0, 0); PG8_STAGE(PG8_SA(1, 1), a1 + hstep, voffA);
;             PG8_WAIT_V(8); PG8_WAIT_L(0); PG8_BAR; PG8_MMA(0, 0, At, B0); PG8_MMA(0, 1, At, B1); PG8_BAR; PG8_SCHED;
;             PG8_LDA(At, 0, 1); PG8_STAGE(PG8_SB(0, 0), b2, voffB); PG8_STAGE(PG8_SB(0, 1), b2 + hstep, voffB); PG8_STAGE(PG8_SA(0, 0), a2, voffA);
;             PG8_WAIT_V(8); PG8_WAIT_L(0); PG8_BAR; PG8_MMA(1, 0, At, B0); PG8_MMA(1, 1, At, B1); PG8_BAR; PG8_SCHED;
;             PG8_LDB(B0, 1, 0); PG8_LDB(B1, 1, 1); PG8_SCHED; PG8_LDA(At, 1, 0); PG8_STAGE(PG8_SA(0, 1), a2 + hstep, voffA);
.Lprio_skip_1:
.LBB0_559:
	v_readfirstlane_b32 s100, v130
	v_readfirstlane_b32 s101, v131
	s_nop 1
	s_sub_u32 s100, s100, 0x10000000
	s_subb_u32 s101, s101, 0
	s_add_i32 s47, s44, 0xfff80080
	s_cmp_eq_u32 s46, 28
	s_cselect_b32 s83, s36, s47
	s_cselect_b32 s47, s37, s45
	s_add_i32 s84, 0, 0x10000
	v_add_u32_e32 v0, s84, v138
	s_add_i32 s86, 0, 0x14000
	ds_read_b128 v[140:143], v0
	ds_read_b128 v[144:147], v0 offset:1024
	ds_read_b128 v[148:151], v0 offset:2048
	ds_read_b128 v[152:155], v0 offset:3072
	v_add_u32_e32 v0, s86, v138
	ds_read_b128 v[156:159], v0
	ds_read_b128 v[160:163], v0 offset:1024
	ds_read_b128 v[164:167], v0 offset:2048
	ds_read_b128 v[168:171], v0 offset:3072
	s_add_i32 s82, s83, 0x80
	s_mov_b32 s87, s44
	ds_read_b128 v[172:175], v139
	ds_read_b128 v[176:179], v139 offset:1024
	ds_read_b128 v[180:183], v139 offset:2048
	ds_read_b128 v[184:187], v139 offset:3072
	ds_read_b128 v[188:191], v139 offset:4096
	ds_read_b128 v[192:195], v139 offset:5120
	ds_read_b128 v[196:199], v139 offset:6144
	ds_read_b128 v[200:203], v139 offset:7168
	s_add_i32 m0, s9, 0xc000
	s_add_i32 vcc_lo, s87, 0x10000000
	s_add_u32 vcc_lo, s100, vcc_lo
	s_addc_u32 vcc_hi, s101, 0
	global_load_lds_dwordx4 v134, vcc
	s_add_i32 m0, s9, 0xe000
	s_nop 0
	global_load_lds_dwordx4 v136, vcc
	s_waitcnt vmcnt(8)
	s_waitcnt lgkmcnt(0)
	s_barrier
	s_waitcnt lgkmcnt(0)
	v_mfma_f32_16x16x128_f8f6f4 v[126:129], v[140:147], v[172:179], v[126:129]
	v_mfma_f32_16x16x128_f8f6f4 v[122:125], v[148:155], v[172:179], v[122:125]
	v_mfma_f32_16x16x128_f8f6f4 v[110:113], v[140:147], v[180:187], v[110:113]
	v_mfma_f32_16x16x128_f8f6f4 v[106:109], v[148:155], v[180:187], v[106:109]
	v_mfma_f32_16x16x128_f8f6f4 v[204:207], v[140:147], v[188:195], v[94:97]
	v_mfma_f32_16x16x128_f8f6f4 v[208:211], v[148:155], v[188:195], v[90:93]
	v_mfma_f32_16x16x128_f8f6f4 v[212:215], v[140:147], v[196:203], v[78:81]
	v_mfma_f32_16x16x128_f8f6f4 v[216:219], v[148:155], v[196:203], v[74:77]
	v_mfma_f32_16x16x128_f8f6f4 v[118:121], v[156:163], v[172:179], v[118:121]
	v_mfma_f32_16x16x128_f8f6f4 v[114:117], v[164:171], v[172:179], v[114:117]
	v_mfma_f32_16x16x128_f8f6f4 v[102:105], v[156:163], v[180:187], v[102:105]
	v_mfma_f32_16x16x128_f8f6f4 v[98:101], v[164:171], v[180:187], v[98:101]
	v_mfma_f32_16x16x128_f8f6f4 v[172:175], v[156:163], v[188:195], v[86:89]
	v_mfma_f32_16x16x128_f8f6f4 v[176:179], v[164:171], v[188:195], v[82:85]
	v_mfma_f32_16x16x128_f8f6f4 v[180:183], v[156:163], v[196:203], v[70:73]
	v_mfma_f32_16x16x128_f8f6f4 v[184:187], v[164:171], v[196:203], v[66:69]
	s_barrier
	s_mov_b32 s87, s47
	s_nop 3
	ds_read_b128 v[66:69], v139 offset:16384
	ds_read_b128 v[70:73], v139 offset:17408
	ds_read_b128 v[74:77], v139 offset:18432
	ds_read_b128 v[78:81], v139 offset:19456
	ds_read_b128 v[82:85], v139 offset:20480
	ds_read_b128 v[86:89], v139 offset:21504
	ds_read_b128 v[90:93], v139 offset:22528
	ds_read_b128 v[94:97], v139 offset:23552
	s_add_i32 s84, s84, s7
	s_add_i32 vcc_lo, s87, 0x10000000
	s_add_u32 vcc_lo, s100, vcc_lo
	s_addc_u32 vcc_hi, s101, 0
	s_mov_b32 m0, s84
	s_nop 0
	global_load_lds_dwordx4 v135, vcc
	s_add_i32 m0, s84, 0x2000
	s_add_i32 s84, s47, 0x80000
	global_load_lds_dwordx4 v137, vcc
	s_add_i32 s86, s86, s7
	s_add_i32 vcc_lo, s84, 0x10000000
	s_add_u32 vcc_lo, s100, vcc_lo
	s_addc_u32 vcc_hi, s101, 0
	s_mov_b32 m0, s86
	s_nop 0
	global_load_lds_dwordx4 v135, vcc
	s_add_i32 m0, s86, 0x2000
	s_mov_b32 s84, s83
	global_load_lds_dwordx4 v137, vcc
	s_mov_b32 m0, s9
	s_add_i32 vcc_lo, s84, 0x10000000
	s_add_u32 vcc_lo, s100, vcc_lo
	s_addc_u32 vcc_hi, s101, 0
	global_load_lds_dwordx4 v134, vcc
	s_mov_b32 m0, s11
	s_nop 0
	global_load_lds_dwordx4 v136, vcc
	s_waitcnt vmcnt(8)
	s_waitcnt lgkmcnt(0)
	s_barrier
	s_waitcnt lgkmcnt(0)
	v_mfma_f32_16x16x128_f8f6f4 v[62:65], v[140:147], v[66:73], v[62:65]
	v_mfma_f32_16x16x128_f8f6f4 v[58:61], v[148:155], v[66:73], v[58:61]
	v_mfma_f32_16x16x128_f8f6f4 v[188:191], v[140:147], v[74:81], v[46:49]
	v_mfma_f32_16x16x128_f8f6f4 v[192:195], v[148:155], v[74:81], v[42:45]
	v_mfma_f32_16x16x128_f8f6f4 v[196:199], v[140:147], v[82:89], v[30:33]
	v_mfma_f32_16x16x128_f8f6f4 v[200:203], v[148:155], v[82:89], v[26:29]
	v_mfma_f32_16x16x128_f8f6f4 v[220:223], v[140:147], v[90:97], v[14:17]
	v_mfma_f32_16x16x128_f8f6f4 v[224:227], v[148:155], v[90:97], v[10:13]
	v_mfma_f32_16x16x128_f8f6f4 v[54:57], v[156:163], v[66:73], v[54:57]
	v_mfma_f32_16x16x128_f8f6f4 v[50:53], v[164:171], v[66:73], v[50:53]
	v_mfma_f32_16x16x128_f8f6f4 v[228:231], v[156:163], v[74:81], v[38:41]
	v_mfma_f32_16x16x128_f8f6f4 v[232:235], v[164:171], v[74:81], v[34:37]
	v_mfma_f32_16x16x128_f8f6f4 v[236:239], v[156:163], v[82:89], v[22:25]
	v_mfma_f32_16x16x128_f8f6f4 v[246:249], v[164:171], v[82:89], v[18:21]
	v_mfma_f32_16x16x128_f8f6f4 v[250:253], v[156:163], v[90:97], v[6:9]
	v_mfma_f32_16x16x128_f8f6f4 v[240:243], v[164:171], v[90:97], v[2:5]
	s_barrier
	s_add_i32 s84, 0, 0x18000
	v_add_u32_e32 v0, s84, v138
	s_add_i32 s86, 0, 0x1c000
	s_nop 1
	ds_read_b128 v[2:5], v0
	ds_read_b128 v[6:9], v0 offset:1024
	ds_read_b128 v[18:21], v0 offset:2048
	ds_read_b128 v[22:25], v0 offset:3072
	v_add_u32_e32 v0, s86, v138
	ds_read_b128 v[140:143], v0
	ds_read_b128 v[144:147], v0 offset:1024
	ds_read_b128 v[148:151], v0 offset:2048
	ds_read_b128 v[152:155], v0 offset:3072
	s_add_i32 s83, s83, 0x80000
	ds_read_b128 v[10:13], v139 offset:32768
	ds_read_b128 v[14:17], v139 offset:33792
	ds_read_b128 v[26:29], v139 offset:34816
	ds_read_b128 v[30:33], v139 offset:35840
	ds_read_b128 v[34:37], v139 offset:36864
	ds_read_b128 v[38:41], v139 offset:37888
	ds_read_b128 v[42:45], v139 offset:38912
	ds_read_b128 v[46:49], v139 offset:39936
	s_mov_b32 m0, s12
	s_add_i32 vcc_lo, s83, 0x10000000
	s_add_u32 vcc_lo, s100, vcc_lo
	s_addc_u32 vcc_hi, s101, 0
	global_load_lds_dwordx4 v134, vcc
	s_mov_b32 m0, s13
	s_nop 0
	global_load_lds_dwordx4 v136, vcc
	s_waitcnt vmcnt(8)
	s_waitcnt lgkmcnt(0)
	s_barrier
; #define GAS __attribute__((address_space(1)))
; __device__ __forceinline__ unsigned gate_pk4(const f32x4& g) { return gate_q8(g[0]) | (gate_q8(g[1]) << 8) | (gate_q8(g[2]) << 16) | (gate_q8(g[3]) << 24); }
; #define PG8_WAIT_V(n) asm volatile("s_waitcnt vmcnt(" #n ")" ::: "memory")
; #define PG8_WAIT_L(n) asm volatile("s_waitcnt lgkmcnt(" #n ")" ::: "memory")
;     ...
;             PG8_LDB(B0, 0, 0); PG8_LDB(B1, 0, 1); PG8_SCHED; PG8_LDA(At, 0, 0); PG8_STAGE(PG8_SA(1, 1), a1 + hstep, voffA);
;             PG8_WAIT_V(8); PG8_WAIT_L(0); PG8_BAR; PG8_MMA(0, 0, At, B0); PG8_MMA(0, 1, At, B1); PG8_BAR; PG8_SCHED;
;             PG8_LDA(At, 0, 1); PG8_STAGE(PG8_SB(0, 0), b2, voffB); PG8_STAGE(PG8_SB(0, 1), b2 + hstep, voffB); PG8_STAGE(PG8_SA(0, 0), a2, voffA);
;             PG8_WAIT_V(8); PG8_WAIT_L(0); PG8_BAR; PG8_MMA(1, 0, At, B0); PG8_MMA(1, 1, At, B1); PG8_BAR; PG8_SCHED;
;             PG8_LDB(B0, 1, 0); PG8_LDB(B1, 1, 1); PG8_SCHED; PG8_LDA(At, 1, 0); PG8_STAGE(PG8_SA(0, 1), a2 + hstep, voffA);
;             PG8_WAIT_V(8); PG8_WAIT_L(0); PG8_BAR; PG8_MMA(0, 0, At, B0); PG8_MMA(0, 1, At, B1); PG8_BAR; PG8_SCHED;
;             PG8_LDA(At, 1, 1); PG8_STAGE(PG8_SB(1, 0), b3, voffB); PG8_STAGE(PG8_SB(1, 1), b3 + hstep, voffB); PG8_STAGE(PG8_SA(1, 0), a3, voffA);
;             PG8_WAIT_V(8); PG8_WAIT_L(0); PG8_BAR; PG8_MMA(1, 0, At, B0); PG8_MMA(1, 1, At, B1); PG8_BAR; PG8_SCHED;
;     __device__ __forceinline__ void operator()(const f32x4 (&acc)[2][2][4][2], const pg8::GUnit& u, int wr, int wc, int fr, int fq) const {
;     ...
;         GAS unsigned char* gb = (GAS unsigned char*)P + (size_t)(u.pm * 256 + (wr * 4 + wc) * 32 + fq) * (INW * 2) + (GA * 2 + u.pn * 256 + fr * 16);
; #pragma unroll
;         for (int ai = 0; ai < 2; ++ai)
; #pragma unroll
;             for (int m = 0; m < 4; ++m) { u32x4 w; unsigned wq[4];
; #pragma unroll
;                 for (int bj = 0; bj < 2; ++bj)
; #pragma unroll
;                     for (int n = 0; n < 2; ++n) { f32x4 v = acc[ai][bj][m][n];
; #pragma unroll
;                         for (int j = 0; j < 4; ++j) v[j] = __builtin_amdgcn_rcpf(1.0f + __builtin_amdgcn_exp2f(v[j] * (-LOG2E * G8_DESCALE)));
;                         wq[bj * 2 + n] = gate_pk4(v); }
;                 w.x = wq[0]; w.y = wq[1]; w.z = wq[2]; w.w = wq[3];
;                 *(GAS u32x4*)(gb + (size_t)((ai * 4 + m) * 4) * (INW * 2)) = w; }
	s_waitcnt lgkmcnt(0)
	v_mfma_f32_16x16x128_f8f6f4 v[126:129], v[2:9], v[10:17], v[126:129]
	v_mfma_f32_16x16x128_f8f6f4 v[122:125], v[18:25], v[10:17], v[122:125]
	v_mfma_f32_16x16x128_f8f6f4 v[110:113], v[2:9], v[26:33], v[110:113]
	v_mfma_f32_16x16x128_f8f6f4 v[106:109], v[18:25], v[26:33], v[106:109]
	v_mfma_f32_16x16x128_f8f6f4 v[94:97], v[2:9], v[34:41], v[204:207]
	v_mfma_f32_16x16x128_f8f6f4 v[90:93], v[18:25], v[34:41], v[208:211]
	v_mfma_f32_16x16x128_f8f6f4 v[78:81], v[2:9], v[42:49], v[212:215]
	v_mfma_f32_16x16x128_f8f6f4 v[74:77], v[18:25], v[42:49], v[216:219]
	v_mfma_f32_16x16x128_f8f6f4 v[118:121], v[140:147], v[10:17], v[118:121]
	v_mfma_f32_16x16x128_f8f6f4 v[114:117], v[148:155], v[10:17], v[114:117]
	v_mfma_f32_16x16x128_f8f6f4 v[102:105], v[140:147], v[26:33], v[102:105]
	v_mfma_f32_16x16x128_f8f6f4 v[98:101], v[148:155], v[26:33], v[98:101]
	v_mfma_f32_16x16x128_f8f6f4 v[86:89], v[140:147], v[34:41], v[172:175]
	v_mfma_f32_16x16x128_f8f6f4 v[82:85], v[148:155], v[34:41], v[176:179]
	v_mfma_f32_16x16x128_f8f6f4 v[70:73], v[140:147], v[42:49], v[180:183]
	v_mfma_f32_16x16x128_f8f6f4 v[66:69], v[148:155], v[42:49], v[184:187]
	s_barrier
	s_add_i32 s83, s47, 0x80
	ds_read_b128 v[34:37], v139 offset:49152
	ds_read_b128 v[38:41], v139 offset:50176
	ds_read_b128 v[156:159], v139 offset:51200
	ds_read_b128 v[160:163], v139 offset:52224
	ds_read_b128 v[164:167], v139 offset:53248
	ds_read_b128 v[168:171], v139 offset:54272
	ds_read_b128 v[172:175], v139 offset:55296
	ds_read_b128 v[176:179], v139 offset:56320
	s_add_i32 s84, s84, s7
	s_add_i32 vcc_lo, s83, 0x10000000
	s_add_u32 vcc_lo, s100, vcc_lo
	s_addc_u32 vcc_hi, s101, 0
	s_mov_b32 m0, s84
	s_nop 0
	global_load_lds_dwordx4 v135, vcc
	s_add_i32 m0, s84, 0x2000
	s_add_i32 s47, s47, 0x80080
	global_load_lds_dwordx4 v137, vcc
	s_add_i32 s83, s86, s7
	s_add_i32 vcc_lo, s47, 0x10000000
	s_add_u32 vcc_lo, s100, vcc_lo
	s_addc_u32 vcc_hi, s101, 0
	s_mov_b32 m0, s83
	s_nop 0
	global_load_lds_dwordx4 v135, vcc
	s_add_i32 m0, s83, 0x2000
	s_nop 0
	global_load_lds_dwordx4 v137, vcc
	s_mov_b32 m0, s18
	s_add_i32 vcc_lo, s82, 0x10000000
	s_add_u32 vcc_lo, s100, vcc_lo
	s_addc_u32 vcc_hi, s101, 0
	global_load_lds_dwordx4 v134, vcc
	s_mov_b32 m0, s22
	s_nop 0
	global_load_lds_dwordx4 v136, vcc
	s_waitcnt vmcnt(8)
	s_waitcnt lgkmcnt(0)
	s_barrier
	s_waitcnt lgkmcnt(0)
	v_mfma_f32_16x16x128_f8f6f4 v[62:65], v[2:9], v[34:41], v[62:65]
	v_mfma_f32_16x16x128_f8f6f4 v[58:61], v[18:25], v[34:41], v[58:61]
	v_mfma_f32_16x16x128_f8f6f4 v[46:49], v[2:9], v[156:163], v[188:191]
	v_mfma_f32_16x16x128_f8f6f4 v[42:45], v[18:25], v[156:163], v[192:195]
	v_mfma_f32_16x16x128_f8f6f4 v[30:33], v[2:9], v[164:171], v[196:199]
	v_mfma_f32_16x16x128_f8f6f4 v[26:29], v[18:25], v[164:171], v[200:203]
	v_mfma_f32_16x16x128_f8f6f4 v[14:17], v[2:9], v[172:179], v[220:223]
	v_mfma_f32_16x16x128_f8f6f4 v[10:13], v[18:25], v[172:179], v[224:227]
	v_mfma_f32_16x16x128_f8f6f4 v[54:57], v[140:147], v[34:41], v[54:57]
	v_mfma_f32_16x16x128_f8f6f4 v[50:53], v[148:155], v[34:41], v[50:53]
	v_mfma_f32_16x16x128_f8f6f4 v[38:41], v[140:147], v[156:163], v[228:231]
	v_mfma_f32_16x16x128_f8f6f4 v[34:37], v[148:155], v[156:163], v[232:235]
	v_mfma_f32_16x16x128_f8f6f4 v[22:25], v[140:147], v[164:171], v[236:239]
	v_mfma_f32_16x16x128_f8f6f4 v[18:21], v[148:155], v[164:171], v[246:249]
	v_mfma_f32_16x16x128_f8f6f4 v[6:9], v[140:147], v[172:179], v[250:253]
	v_mfma_f32_16x16x128_f8f6f4 v[2:5], v[148:155], v[172:179], v[240:243]
	s_add_i32 s46, s46, 2
	s_addk_i32 s44, 0x100
	s_addk_i32 s45, 0x100
	s_cmp_gt_u32 s46, 29
	s_barrier
	s_cbranch_scc0 .LBB0_559
	s_setprio 0
	v_mbcnt_lo_u32_b32 v0, -1, 0
	v_mbcnt_hi_u32_b32 v0, -1, v0
	s_lshl_b32 s38, s38, 8
	v_ashrrev_i32_e32 v140, 4, v0
	v_lshlrev_b32_e32 v0, 4, v0
	s_addk_i32 s38, 0x6000
	v_and_b32_e32 v0, 0xf0, v0
	v_or_b32_e32 v142, s38, v0
	v_mul_f32_e32 v0, 0xba38aa3b, v126
	v_mul_f32_e32 v126, 0xba38aa3b, v127
	v_exp_f32_e32 v126, v126
	v_mul_f32_e32 v127, 0xba38aa3b, v128
	v_exp_f32_e32 v127, v127
	v_exp_f32_e32 v0, v0
	v_mul_f32_e32 v128, 0xba38aa3b, v129
	v_add_f32_e32 v126, 1.0, v126
	v_exp_f32_e32 v128, v128
	v_rcp_f32_e32 v126, v126
	v_add_f32_e32 v127, 1.0, v127
	v_add_f32_e32 v0, 1.0, v0
	v_rcp_f32_e32 v127, v127
	v_rcp_f32_e32 v0, v0
	v_add_f32_e32 v128, 1.0, v128
	v_rcp_f32_e32 v128, v128
	v_fma_f32 v126, v126, s49, 0.5
	v_max_f32_e32 v126, 1.0, v126
	v_cvt_u32_f32_e32 v129, v126
	v_fma_f32 v126, v127, s49, 0.5
	v_fma_f32 v0, v0, s49, 0.5
	v_max_f32_e32 v126, 1.0, v126
	v_max_f32_e32 v0, 1.0, v0
	v_cvt_u32_f32_sdwa v144, v126 dst_sel:WORD_1 dst_unused:UNUSED_PAD src0_sel:DWORD
	v_fma_f32 v126, v128, s49, 0.5
	v_cvt_u32_f32_e32 v0, v0
	v_max_f32_e32 v126, 1.0, v126
	v_mul_f32_e32 v122, 0xba38aa3b, v122
	v_mul_f32_e32 v123, 0xba38aa3b, v123
	v_cvt_u32_f32_sdwa v128, v126 dst_sel:BYTE_3 dst_unused:UNUSED_PAD src0_sel:DWORD
	v_exp_f32_e32 v145, v122
	v_exp_f32_e32 v123, v123
	v_lshl_or_b32 v0, v129, 8, v0
	v_or3_b32 v122, v0, v144, v128
	v_add_f32_e32 v0, 1.0, v145
	v_add_f32_e32 v123, 1.0, v123
	v_mul_f32_e32 v124, 0xba38aa3b, v124
	v_rcp_f32_e32 v0, v0
	v_rcp_f32_e32 v123, v123
	v_mul_f32_e32 v125, 0xba38aa3b, v125
	v_mul_f32_e32 v118, 0xba38aa3b, v118
	v_mul_f32_e32 v119, 0xba38aa3b, v119
	v_exp_f32_e32 v124, v124
	v_exp_f32_e32 v125, v125
	v_exp_f32_e32 v118, v118
	v_exp_f32_e32 v119, v119
	v_mul_f32_e32 v120, 0xba38aa3b, v120
	v_mul_f32_e32 v121, 0xba38aa3b, v121
	v_exp_f32_e32 v120, v120
	v_exp_f32_e32 v121, v121
	v_fma_f32 v0, v0, s49, 0.5
	v_fma_f32 v123, v123, s49, 0.5
	v_add_f32_e32 v124, 1.0, v124
	v_max_f32_e32 v0, 1.0, v0
	v_max_f32_e32 v123, 1.0, v123
; #define GAS __attribute__((address_space(1)))
; __device__ __forceinline__ unsigned gate_q8(float g) { return (unsigned)fmaxf(g * 255.0f + 0.5f, 1.0f); }
; __device__ __forceinline__ unsigned gate_pk4(const f32x4& g) { return gate_q8(g[0]) | (gate_q8(g[1]) << 8) | (gate_q8(g[2]) << 16) | (gate_q8(g[3]) << 24); }
;     __device__ __forceinline__ void operator()(const f32x4 (&acc)[2][2][4][2], const pg8::GUnit& u, int wr, int wc, int fr, int fq) const {
;     ...
;         for (int ai = 0; ai < 2; ++ai)
; #pragma unroll
;             for (int m = 0; m < 4; ++m) { u32x4 w; unsigned wq[4];
; #pragma unroll
;                 for (int bj = 0; bj < 2; ++bj)
; #pragma unroll
;                     for (int n = 0; n < 2; ++n) { f32x4 v = acc[ai][bj][m][n];
; #pragma unroll
;                         for (int j = 0; j < 4; ++j) v[j] = __builtin_amdgcn_rcpf(1.0f + __builtin_amdgcn_exp2f(v[j] * (-LOG2E * G8_DESCALE)));
;                         wq[bj * 2 + n] = gate_pk4(v); }
;                 w.x = wq[0]; w.y = wq[1]; w.z = wq[2]; w.w = wq[3];
;                 *(GAS u32x4*)(gb + (size_t)((ai * 4 + m) * 4) * (INW * 2)) = w; }
	v_add_f32_e32 v125, 1.0, v125
	v_add_f32_e32 v118, 1.0, v118
	v_add_f32_e32 v119, 1.0, v119
	v_cvt_u32_f32_e32 v0, v0
	v_cvt_u32_f32_e32 v123, v123
	v_rcp_f32_e32 v124, v124
	v_rcp_f32_e32 v125, v125
	v_rcp_f32_e32 v118, v118
	v_rcp_f32_e32 v119, v119
	v_add_f32_e32 v120, 1.0, v120
	v_add_f32_e32 v121, 1.0, v121
	v_rcp_f32_e32 v120, v120
	v_rcp_f32_e32 v121, v121
	v_lshl_or_b32 v0, v123, 8, v0
	v_fma_f32 v123, v124, s49, 0.5
	v_fma_f32 v124, v125, s49, 0.5
	v_fma_f32 v118, v118, s49, 0.5
	v_fma_f32 v119, v119, s49, 0.5
	v_max_f32_e32 v123, 1.0, v123
	v_max_f32_e32 v124, 1.0, v124
	v_max_f32_e32 v118, 1.0, v118
	v_max_f32_e32 v119, 1.0, v119
	v_fma_f32 v120, v120, s49, 0.5
	v_fma_f32 v121, v121, s49, 0.5
	v_cvt_u32_f32_sdwa v123, v123 dst_sel:WORD_1 dst_unused:UNUSED_PAD src0_sel:DWORD
	v_cvt_u32_f32_sdwa v124, v124 dst_sel:BYTE_3 dst_unused:UNUSED_PAD src0_sel:DWORD
	v_cvt_u32_f32_e32 v118, v118
	v_cvt_u32_f32_e32 v119, v119
	v_max_f32_e32 v120, 1.0, v120
	v_max_f32_e32 v121, 1.0, v121
	v_mul_f32_e32 v114, 0xba38aa3b, v114
	v_cvt_u32_f32_sdwa v120, v120 dst_sel:WORD_1 dst_unused:UNUSED_PAD src0_sel:DWORD
	v_cvt_u32_f32_sdwa v121, v121 dst_sel:BYTE_3 dst_unused:UNUSED_PAD src0_sel:DWORD
	v_exp_f32_e32 v114, v114
	v_or3_b32 v123, v0, v123, v124
	v_lshl_or_b32 v0, v119, 8, v118
	v_or3_b32 v124, v0, v120, v121
	v_add_f32_e32 v0, 1.0, v114
	v_mul_f32_e32 v114, 0xba38aa3b, v115
	v_exp_f32_e32 v114, v114
	v_mul_f32_e32 v115, 0xba38aa3b, v116
	v_rcp_f32_e32 v0, v0
	v_mul_f32_e32 v116, 0xba38aa3b, v117
	v_add_f32_e32 v114, 1.0, v114
	v_rcp_f32_e32 v114, v114
	v_exp_f32_e32 v115, v115
	v_exp_f32_e32 v116, v116
	v_fma_f32 v0, v0, s49, 0.5
	v_fma_f32 v114, v114, s49, 0.5
	v_add_f32_e32 v115, 1.0, v115
	v_max_f32_e32 v0, 1.0, v0
	v_max_f32_e32 v114, 1.0, v114
	v_add_f32_e32 v116, 1.0, v116
	v_cvt_u32_f32_e32 v0, v0
	v_cvt_u32_f32_e32 v114, v114
	v_rcp_f32_e32 v115, v115
	v_rcp_f32_e32 v116, v116
	v_mul_f32_e32 v110, 0xba38aa3b, v110
	v_lshl_or_b32 v0, v114, 8, v0
	v_fma_f32 v114, v115, s49, 0.5
	v_fma_f32 v115, v116, s49, 0.5
	v_max_f32_e32 v114, 1.0, v114
	v_max_f32_e32 v115, 1.0, v115
	v_mul_f32_e32 v111, 0xba38aa3b, v111
	v_cvt_u32_f32_sdwa v114, v114 dst_sel:WORD_1 dst_unused:UNUSED_PAD src0_sel:DWORD
	v_cvt_u32_f32_sdwa v115, v115 dst_sel:BYTE_3 dst_unused:UNUSED_PAD src0_sel:DWORD
	v_exp_f32_e32 v110, v110
	v_exp_f32_e32 v111, v111
	v_mul_f32_e32 v106, 0xba38aa3b, v106
	v_or3_b32 v125, v0, v114, v115
	v_add_f32_e32 v0, 1.0, v110
	v_add_f32_e32 v110, 1.0, v111
	v_mul_f32_e32 v111, 0xba38aa3b, v112
	v_mul_f32_e32 v112, 0xba38aa3b, v113
	v_exp_f32_e32 v111, v111
	v_exp_f32_e32 v112, v112
	v_rcp_f32_e32 v0, v0
	v_rcp_f32_e32 v110, v110
	v_add_f32_e32 v111, 1.0, v111
	v_add_f32_e32 v112, 1.0, v112
	v_rcp_f32_e32 v111, v111
	v_rcp_f32_e32 v112, v112
	v_fma_f32 v0, v0, s49, 0.5
	v_fma_f32 v110, v110, s49, 0.5
	v_max_f32_e32 v0, 1.0, v0
	v_max_f32_e32 v110, 1.0, v110
	v_fma_f32 v111, v111, s49, 0.5
	v_fma_f32 v112, v112, s49, 0.5
	v_cvt_u32_f32_e32 v0, v0
	v_cvt_u32_f32_e32 v110, v110
	v_max_f32_e32 v111, 1.0, v111
	v_max_f32_e32 v112, 1.0, v112
	v_mul_f32_e32 v107, 0xba38aa3b, v107
	v_cvt_u32_f32_sdwa v111, v111 dst_sel:WORD_1 dst_unused:UNUSED_PAD src0_sel:DWORD
	v_cvt_u32_f32_sdwa v112, v112 dst_sel:BYTE_3 dst_unused:UNUSED_PAD src0_sel:DWORD
	v_exp_f32_e32 v113, v106
	v_exp_f32_e32 v107, v107
	v_lshl_or_b32 v0, v110, 8, v0
	v_or3_b32 v106, v0, v111, v112
	v_add_f32_e32 v0, 1.0, v113
	v_add_f32_e32 v107, 1.0, v107
	v_mul_f32_e32 v108, 0xba38aa3b, v108
	v_rcp_f32_e32 v0, v0
	v_rcp_f32_e32 v107, v107
	v_mul_f32_e32 v109, 0xba38aa3b, v109
	v_exp_f32_e32 v108, v108
	v_exp_f32_e32 v109, v109
	v_fma_f32 v0, v0, s49, 0.5
	v_fma_f32 v107, v107, s49, 0.5
	v_add_f32_e32 v108, 1.0, v108
	v_max_f32_e32 v0, 1.0, v0
	v_max_f32_e32 v107, 1.0, v107
	v_add_f32_e32 v109, 1.0, v109
	v_cvt_u32_f32_e32 v0, v0
	v_cvt_u32_f32_e32 v107, v107
	v_rcp_f32_e32 v108, v108
	v_rcp_f32_e32 v109, v109
	v_mul_f32_e32 v102, 0xba38aa3b, v102
	v_lshl_or_b32 v0, v107, 8, v0
	v_fma_f32 v107, v108, s49, 0.5
	v_fma_f32 v108, v109, s49, 0.5
	v_max_f32_e32 v107, 1.0, v107
	v_max_f32_e32 v108, 1.0, v108
	v_mul_f32_e32 v103, 0xba38aa3b, v103
	v_cvt_u32_f32_sdwa v107, v107 dst_sel:WORD_1 dst_unused:UNUSED_PAD src0_sel:DWORD
	v_cvt_u32_f32_sdwa v108, v108 dst_sel:BYTE_3 dst_unused:UNUSED_PAD src0_sel:DWORD
	v_exp_f32_e32 v102, v102
	v_exp_f32_e32 v103, v103
	v_mul_f32_e32 v98, 0xba38aa3b, v98
	v_or3_b32 v107, v0, v107, v108
	v_add_f32_e32 v0, 1.0, v102
	v_add_f32_e32 v102, 1.0, v103
	v_mul_f32_e32 v103, 0xba38aa3b, v104
	v_mul_f32_e32 v104, 0xba38aa3b, v105
	v_mul_f32_e32 v99, 0xba38aa3b, v99
	v_exp_f32_e32 v103, v103
	v_exp_f32_e32 v104, v104
	v_exp_f32_e32 v98, v98
	v_exp_f32_e32 v99, v99
	v_mul_f32_e32 v100, 0xba38aa3b, v100
	v_mul_f32_e32 v101, 0xba38aa3b, v101
	v_exp_f32_e32 v100, v100
	v_exp_f32_e32 v101, v101
	v_rcp_f32_e32 v0, v0
	v_rcp_f32_e32 v102, v102
	v_add_f32_e32 v103, 1.0, v103
	v_add_f32_e32 v104, 1.0, v104
	v_add_f32_e32 v98, 1.0, v98
	v_add_f32_e32 v99, 1.0, v99
	v_rcp_f32_e32 v103, v103
	v_rcp_f32_e32 v104, v104
	v_rcp_f32_e32 v98, v98
	v_rcp_f32_e32 v99, v99
	v_add_f32_e32 v100, 1.0, v100
	v_add_f32_e32 v101, 1.0, v101
	v_rcp_f32_e32 v100, v100
	v_rcp_f32_e32 v101, v101
	v_fma_f32 v0, v0, s49, 0.5
	v_fma_f32 v102, v102, s49, 0.5
	v_max_f32_e32 v0, 1.0, v0
	v_max_f32_e32 v102, 1.0, v102
	v_fma_f32 v103, v103, s49, 0.5
	v_fma_f32 v104, v104, s49, 0.5
	v_fma_f32 v98, v98, s49, 0.5
	v_fma_f32 v99, v99, s49, 0.5
	v_cvt_u32_f32_e32 v0, v0
	v_cvt_u32_f32_e32 v102, v102
	v_max_f32_e32 v103, 1.0, v103
	v_max_f32_e32 v104, 1.0, v104
	v_max_f32_e32 v98, 1.0, v98
	v_max_f32_e32 v99, 1.0, v99
; #define GAS __attribute__((address_space(1)))
; __device__ __forceinline__ unsigned gate_q8(float g) { return (unsigned)fmaxf(g * 255.0f + 0.5f, 1.0f); }
; __device__ __forceinline__ unsigned gate_pk4(const f32x4& g) { return gate_q8(g[0]) | (gate_q8(g[1]) << 8) | (gate_q8(g[2]) << 16) | (gate_q8(g[3]) << 24); }
;     __device__ __forceinline__ void operator()(const f32x4 (&acc)[2][2][4][2], const pg8::GUnit& u, int wr, int wc, int fr, int fq) const {
;     ...
;         for (int ai = 0; ai < 2; ++ai)
; #pragma unroll
;             for (int m = 0; m < 4; ++m) { u32x4 w; unsigned wq[4];
; #pragma unroll
;                 for (int bj = 0; bj < 2; ++bj)
; #pragma unroll
;                     for (int n = 0; n < 2; ++n) { f32x4 v = acc[ai][bj][m][n];
; #pragma unroll
;                         for (int j = 0; j < 4; ++j) v[j] = __builtin_amdgcn_rcpf(1.0f + __builtin_amdgcn_exp2f(v[j] * (-LOG2E * G8_DESCALE)));
;                         wq[bj * 2 + n] = gate_pk4(v); }
;                 w.x = wq[0]; w.y = wq[1]; w.z = wq[2]; w.w = wq[3];
;                 *(GAS u32x4*)(gb + (size_t)((ai * 4 + m) * 4) * (INW * 2)) = w; }
	v_fma_f32 v100, v100, s49, 0.5
	v_fma_f32 v101, v101, s49, 0.5
	v_cvt_u32_f32_sdwa v103, v103 dst_sel:WORD_1 dst_unused:UNUSED_PAD src0_sel:DWORD
	v_cvt_u32_f32_sdwa v104, v104 dst_sel:BYTE_3 dst_unused:UNUSED_PAD src0_sel:DWORD
	v_cvt_u32_f32_e32 v98, v98
	v_cvt_u32_f32_e32 v99, v99
	v_max_f32_e32 v100, 1.0, v100
	v_max_f32_e32 v101, 1.0, v101
	v_cvt_u32_f32_sdwa v100, v100 dst_sel:WORD_1 dst_unused:UNUSED_PAD src0_sel:DWORD
	v_cvt_u32_f32_sdwa v101, v101 dst_sel:BYTE_3 dst_unused:UNUSED_PAD src0_sel:DWORD
	v_lshl_or_b32 v0, v102, 8, v0
	v_or3_b32 v108, v0, v103, v104
	v_lshl_or_b32 v0, v99, 8, v98
	v_or3_b32 v109, v0, v100, v101
	v_mul_f32_e32 v0, 0xba38aa3b, v94
	v_mul_f32_e32 v94, 0xba38aa3b, v95
	v_exp_f32_e32 v0, v0
	v_exp_f32_e32 v98, v94
	v_mul_f32_e32 v96, 0xba38aa3b, v96
	v_mul_f32_e32 v97, 0xba38aa3b, v97
	v_exp_f32_e32 v96, v96
	v_exp_f32_e32 v97, v97
	v_add_f32_e32 v0, 1.0, v0
	v_add_f32_e32 v98, 1.0, v98
	v_rcp_f32_e32 v0, v0
	v_rcp_f32_e32 v98, v98
	v_add_f32_e32 v96, 1.0, v96
	v_add_f32_e32 v97, 1.0, v97
	v_rcp_f32_e32 v96, v96
	v_rcp_f32_e32 v97, v97
	v_fma_f32 v0, v0, s49, 0.5
	v_fma_f32 v98, v98, s49, 0.5
	v_max_f32_e32 v0, 1.0, v0
	v_max_f32_e32 v98, 1.0, v98
	v_fma_f32 v96, v96, s49, 0.5
	v_fma_f32 v97, v97, s49, 0.5
	v_cvt_u32_f32_e32 v0, v0
	v_cvt_u32_f32_e32 v98, v98
	v_max_f32_e32 v96, 1.0, v96
	v_max_f32_e32 v97, 1.0, v97
	v_mul_f32_e32 v90, 0xba38aa3b, v90
	v_mul_f32_e32 v91, 0xba38aa3b, v91
	v_cvt_u32_f32_sdwa v96, v96 dst_sel:WORD_1 dst_unused:UNUSED_PAD src0_sel:DWORD
	v_cvt_u32_f32_sdwa v97, v97 dst_sel:BYTE_3 dst_unused:UNUSED_PAD src0_sel:DWORD
	v_exp_f32_e32 v99, v90
	v_exp_f32_e32 v91, v91
	v_lshl_or_b32 v0, v98, 8, v0
	v_or3_b32 v90, v0, v96, v97
	v_add_f32_e32 v0, 1.0, v99
	v_add_f32_e32 v91, 1.0, v91
	v_mul_f32_e32 v92, 0xba38aa3b, v92
	v_rcp_f32_e32 v0, v0
	v_rcp_f32_e32 v91, v91
	v_mul_f32_e32 v93, 0xba38aa3b, v93
	v_exp_f32_e32 v92, v92
	v_exp_f32_e32 v93, v93
	v_fma_f32 v0, v0, s49, 0.5
	v_fma_f32 v91, v91, s49, 0.5
	v_add_f32_e32 v92, 1.0, v92
	v_max_f32_e32 v0, 1.0, v0
	v_max_f32_e32 v91, 1.0, v91
	v_add_f32_e32 v93, 1.0, v93
	v_cvt_u32_f32_e32 v0, v0
	v_cvt_u32_f32_e32 v91, v91
	v_rcp_f32_e32 v92, v92
	v_rcp_f32_e32 v93, v93
	v_mul_f32_e32 v86, 0xba38aa3b, v86
	v_lshl_or_b32 v0, v91, 8, v0
	v_fma_f32 v91, v92, s49, 0.5
	v_fma_f32 v92, v93, s49, 0.5
	v_max_f32_e32 v91, 1.0, v91
	v_max_f32_e32 v92, 1.0, v92
	v_mul_f32_e32 v87, 0xba38aa3b, v87
	v_cvt_u32_f32_sdwa v91, v91 dst_sel:WORD_1 dst_unused:UNUSED_PAD src0_sel:DWORD
	v_cvt_u32_f32_sdwa v92, v92 dst_sel:BYTE_3 dst_unused:UNUSED_PAD src0_sel:DWORD
	v_exp_f32_e32 v86, v86
	v_exp_f32_e32 v87, v87
	v_mul_f32_e32 v82, 0xba38aa3b, v82
	v_or3_b32 v91, v0, v91, v92
	v_add_f32_e32 v0, 1.0, v86
	v_add_f32_e32 v86, 1.0, v87
	v_mul_f32_e32 v87, 0xba38aa3b, v88
	v_mul_f32_e32 v88, 0xba38aa3b, v89
	v_mul_f32_e32 v83, 0xba38aa3b, v83
	v_exp_f32_e32 v87, v87
	v_exp_f32_e32 v88, v88
	v_exp_f32_e32 v82, v82
	v_exp_f32_e32 v83, v83
	v_mul_f32_e32 v84, 0xba38aa3b, v84
	v_mul_f32_e32 v85, 0xba38aa3b, v85
	v_exp_f32_e32 v84, v84
	v_exp_f32_e32 v85, v85
	v_rcp_f32_e32 v0, v0
	v_rcp_f32_e32 v86, v86
	v_add_f32_e32 v87, 1.0, v87
	v_add_f32_e32 v88, 1.0, v88
	v_add_f32_e32 v82, 1.0, v82
	v_add_f32_e32 v83, 1.0, v83
	v_rcp_f32_e32 v87, v87
	v_rcp_f32_e32 v88, v88
	v_rcp_f32_e32 v82, v82
	v_rcp_f32_e32 v83, v83
	v_add_f32_e32 v84, 1.0, v84
	v_add_f32_e32 v85, 1.0, v85
	v_rcp_f32_e32 v84, v84
	v_rcp_f32_e32 v85, v85
	v_fma_f32 v0, v0, s49, 0.5
	v_fma_f32 v86, v86, s49, 0.5
	v_max_f32_e32 v0, 1.0, v0
	v_max_f32_e32 v86, 1.0, v86
	v_fma_f32 v87, v87, s49, 0.5
	v_fma_f32 v88, v88, s49, 0.5
	v_fma_f32 v82, v82, s49, 0.5
	v_fma_f32 v83, v83, s49, 0.5
	v_cvt_u32_f32_e32 v0, v0
	v_cvt_u32_f32_e32 v86, v86
	v_max_f32_e32 v87, 1.0, v87
	v_max_f32_e32 v88, 1.0, v88
	v_max_f32_e32 v82, 1.0, v82
	v_max_f32_e32 v83, 1.0, v83
	v_fma_f32 v84, v84, s49, 0.5
	v_fma_f32 v85, v85, s49, 0.5
	v_cvt_u32_f32_sdwa v87, v87 dst_sel:WORD_1 dst_unused:UNUSED_PAD src0_sel:DWORD
	v_cvt_u32_f32_sdwa v88, v88 dst_sel:BYTE_3 dst_unused:UNUSED_PAD src0_sel:DWORD
	v_cvt_u32_f32_e32 v82, v82
	v_cvt_u32_f32_e32 v83, v83
	v_max_f32_e32 v84, 1.0, v84
	v_max_f32_e32 v85, 1.0, v85
	v_cvt_u32_f32_sdwa v84, v84 dst_sel:WORD_1 dst_unused:UNUSED_PAD src0_sel:DWORD
	v_cvt_u32_f32_sdwa v85, v85 dst_sel:BYTE_3 dst_unused:UNUSED_PAD src0_sel:DWORD
	v_lshl_or_b32 v0, v86, 8, v0
	v_or3_b32 v92, v0, v87, v88
	v_lshl_or_b32 v0, v83, 8, v82
	v_or3_b32 v93, v0, v84, v85
	v_mul_f32_e32 v0, 0xba38aa3b, v78
	v_mul_f32_e32 v78, 0xba38aa3b, v79
	v_exp_f32_e32 v0, v0
	v_exp_f32_e32 v82, v78
	v_mul_f32_e32 v80, 0xba38aa3b, v80
	v_mul_f32_e32 v81, 0xba38aa3b, v81
	v_exp_f32_e32 v80, v80
	v_exp_f32_e32 v81, v81
	v_add_f32_e32 v0, 1.0, v0
	v_add_f32_e32 v82, 1.0, v82
	v_rcp_f32_e32 v0, v0
	v_rcp_f32_e32 v82, v82
	v_add_f32_e32 v80, 1.0, v80
	v_add_f32_e32 v81, 1.0, v81
	v_rcp_f32_e32 v80, v80
	v_rcp_f32_e32 v81, v81
	v_fma_f32 v0, v0, s49, 0.5
	v_fma_f32 v82, v82, s49, 0.5
	v_max_f32_e32 v0, 1.0, v0
	v_max_f32_e32 v82, 1.0, v82
	v_fma_f32 v80, v80, s49, 0.5
	v_fma_f32 v81, v81, s49, 0.5
	v_cvt_u32_f32_e32 v0, v0
	v_cvt_u32_f32_e32 v82, v82
	v_max_f32_e32 v80, 1.0, v80
	v_max_f32_e32 v81, 1.0, v81
	v_mul_f32_e32 v74, 0xba38aa3b, v74
	v_mul_f32_e32 v75, 0xba38aa3b, v75
	v_cvt_u32_f32_sdwa v80, v80 dst_sel:WORD_1 dst_unused:UNUSED_PAD src0_sel:DWORD
	v_cvt_u32_f32_sdwa v81, v81 dst_sel:BYTE_3 dst_unused:UNUSED_PAD src0_sel:DWORD
	v_exp_f32_e32 v83, v74
	v_exp_f32_e32 v75, v75
	v_lshl_or_b32 v0, v82, 8, v0
	v_or3_b32 v74, v0, v80, v81
	v_add_f32_e32 v0, 1.0, v83
	v_add_f32_e32 v75, 1.0, v75
	v_mul_f32_e32 v76, 0xba38aa3b, v76
; #define GAS __attribute__((address_space(1)))
; __device__ __forceinline__ unsigned gate_q8(float g) { return (unsigned)fmaxf(g * 255.0f + 0.5f, 1.0f); }
; __device__ __forceinline__ unsigned gate_pk4(const f32x4& g) { return gate_q8(g[0]) | (gate_q8(g[1]) << 8) | (gate_q8(g[2]) << 16) | (gate_q8(g[3]) << 24); }
;     __device__ __forceinline__ void operator()(const f32x4 (&acc)[2][2][4][2], const pg8::GUnit& u, int wr, int wc, int fr, int fq) const {
;     ...
;         for (int ai = 0; ai < 2; ++ai)
; #pragma unroll
;             for (int m = 0; m < 4; ++m) { u32x4 w; unsigned wq[4];
; #pragma unroll
;                 for (int bj = 0; bj < 2; ++bj)
; #pragma unroll
;                     for (int n = 0; n < 2; ++n) { f32x4 v = acc[ai][bj][m][n];
; #pragma unroll
;                         for (int j = 0; j < 4; ++j) v[j] = __builtin_amdgcn_rcpf(1.0f + __builtin_amdgcn_exp2f(v[j] * (-LOG2E * G8_DESCALE)));
;                         wq[bj * 2 + n] = gate_pk4(v); }
;                 w.x = wq[0]; w.y = wq[1]; w.z = wq[2]; w.w = wq[3];
;                 *(GAS u32x4*)(gb + (size_t)((ai * 4 + m) * 4) * (INW * 2)) = w; }
	v_rcp_f32_e32 v0, v0
	v_rcp_f32_e32 v75, v75
	v_mul_f32_e32 v77, 0xba38aa3b, v77
	v_exp_f32_e32 v76, v76
	v_exp_f32_e32 v77, v77
	v_fma_f32 v0, v0, s49, 0.5
	v_fma_f32 v75, v75, s49, 0.5
	v_add_f32_e32 v76, 1.0, v76
	v_max_f32_e32 v0, 1.0, v0
	v_max_f32_e32 v75, 1.0, v75
	v_add_f32_e32 v77, 1.0, v77
	v_cvt_u32_f32_e32 v0, v0
	v_cvt_u32_f32_e32 v75, v75
	v_rcp_f32_e32 v76, v76
	v_rcp_f32_e32 v77, v77
	v_mul_f32_e32 v70, 0xba38aa3b, v70
	v_lshl_or_b32 v0, v75, 8, v0
	v_fma_f32 v75, v76, s49, 0.5
	v_fma_f32 v76, v77, s49, 0.5
	v_max_f32_e32 v75, 1.0, v75
	v_max_f32_e32 v76, 1.0, v76
	v_mul_f32_e32 v71, 0xba38aa3b, v71
	v_cvt_u32_f32_sdwa v75, v75 dst_sel:WORD_1 dst_unused:UNUSED_PAD src0_sel:DWORD
	v_cvt_u32_f32_sdwa v76, v76 dst_sel:BYTE_3 dst_unused:UNUSED_PAD src0_sel:DWORD
	v_exp_f32_e32 v70, v70
	v_exp_f32_e32 v71, v71
	v_mul_f32_e32 v66, 0xba38aa3b, v66
	v_or3_b32 v75, v0, v75, v76
	v_add_f32_e32 v0, 1.0, v70
	v_add_f32_e32 v70, 1.0, v71
	v_mul_f32_e32 v71, 0xba38aa3b, v72
	v_mul_f32_e32 v72, 0xba38aa3b, v73
	v_mul_f32_e32 v67, 0xba38aa3b, v67
	v_exp_f32_e32 v71, v71
	v_exp_f32_e32 v72, v72
	v_exp_f32_e32 v66, v66
	v_exp_f32_e32 v67, v67
	v_mul_f32_e32 v68, 0xba38aa3b, v68
	v_mul_f32_e32 v69, 0xba38aa3b, v69
	v_exp_f32_e32 v68, v68
	v_exp_f32_e32 v69, v69
	v_rcp_f32_e32 v0, v0
	v_rcp_f32_e32 v70, v70
	v_add_f32_e32 v71, 1.0, v71
	v_add_f32_e32 v72, 1.0, v72
	v_add_f32_e32 v66, 1.0, v66
	v_add_f32_e32 v67, 1.0, v67
	v_rcp_f32_e32 v71, v71
	v_rcp_f32_e32 v72, v72
	v_rcp_f32_e32 v66, v66
	v_rcp_f32_e32 v67, v67
	v_add_f32_e32 v68, 1.0, v68
	v_add_f32_e32 v69, 1.0, v69
	v_rcp_f32_e32 v68, v68
	v_rcp_f32_e32 v69, v69
	v_fma_f32 v0, v0, s49, 0.5
	v_fma_f32 v70, v70, s49, 0.5
	v_max_f32_e32 v0, 1.0, v0
	v_max_f32_e32 v70, 1.0, v70
	v_fma_f32 v71, v71, s49, 0.5
	v_fma_f32 v72, v72, s49, 0.5
	v_fma_f32 v66, v66, s49, 0.5
	v_fma_f32 v67, v67, s49, 0.5
	v_cvt_u32_f32_e32 v0, v0
	v_cvt_u32_f32_e32 v70, v70
	v_max_f32_e32 v71, 1.0, v71
	v_max_f32_e32 v72, 1.0, v72
	v_max_f32_e32 v66, 1.0, v66
	v_max_f32_e32 v67, 1.0, v67
	v_fma_f32 v68, v68, s49, 0.5
	v_fma_f32 v69, v69, s49, 0.5
	v_cvt_u32_f32_sdwa v71, v71 dst_sel:WORD_1 dst_unused:UNUSED_PAD src0_sel:DWORD
	v_cvt_u32_f32_sdwa v72, v72 dst_sel:BYTE_3 dst_unused:UNUSED_PAD src0_sel:DWORD
	v_cvt_u32_f32_e32 v66, v66
	v_cvt_u32_f32_e32 v67, v67
	v_max_f32_e32 v68, 1.0, v68
	v_max_f32_e32 v69, 1.0, v69
	v_cvt_u32_f32_sdwa v68, v68 dst_sel:WORD_1 dst_unused:UNUSED_PAD src0_sel:DWORD
	v_cvt_u32_f32_sdwa v69, v69 dst_sel:BYTE_3 dst_unused:UNUSED_PAD src0_sel:DWORD
	v_lshl_or_b32 v0, v70, 8, v0
	v_or3_b32 v76, v0, v71, v72
	v_lshl_or_b32 v0, v67, 8, v66
	v_or3_b32 v77, v0, v68, v69
	v_mul_f32_e32 v0, 0xba38aa3b, v62
	v_mul_f32_e32 v62, 0xba38aa3b, v63
	v_exp_f32_e32 v0, v0
	v_exp_f32_e32 v66, v62
	v_mul_f32_e32 v64, 0xba38aa3b, v64
	v_mul_f32_e32 v65, 0xba38aa3b, v65
	v_exp_f32_e32 v64, v64
	v_exp_f32_e32 v65, v65
	v_add_f32_e32 v0, 1.0, v0
	v_add_f32_e32 v66, 1.0, v66
	v_rcp_f32_e32 v0, v0
	v_rcp_f32_e32 v66, v66
	v_add_f32_e32 v64, 1.0, v64
	v_add_f32_e32 v65, 1.0, v65
	v_rcp_f32_e32 v64, v64
	v_rcp_f32_e32 v65, v65
	v_fma_f32 v0, v0, s49, 0.5
	v_fma_f32 v66, v66, s49, 0.5
	v_max_f32_e32 v0, 1.0, v0
	v_max_f32_e32 v66, 1.0, v66
	v_fma_f32 v64, v64, s49, 0.5
	v_fma_f32 v65, v65, s49, 0.5
	v_cvt_u32_f32_e32 v0, v0
	v_cvt_u32_f32_e32 v66, v66
	v_max_f32_e32 v64, 1.0, v64
	v_max_f32_e32 v65, 1.0, v65
	v_mul_f32_e32 v58, 0xba38aa3b, v58
	v_mul_f32_e32 v59, 0xba38aa3b, v59
	v_cvt_u32_f32_sdwa v64, v64 dst_sel:WORD_1 dst_unused:UNUSED_PAD src0_sel:DWORD
	v_cvt_u32_f32_sdwa v65, v65 dst_sel:BYTE_3 dst_unused:UNUSED_PAD src0_sel:DWORD
	v_exp_f32_e32 v67, v58
	v_exp_f32_e32 v59, v59
	v_lshl_or_b32 v0, v66, 8, v0
	v_or3_b32 v58, v0, v64, v65
	v_add_f32_e32 v0, 1.0, v67
	v_add_f32_e32 v59, 1.0, v59
	v_mul_f32_e32 v60, 0xba38aa3b, v60
	v_rcp_f32_e32 v0, v0
	v_rcp_f32_e32 v59, v59
	v_mul_f32_e32 v61, 0xba38aa3b, v61
	v_exp_f32_e32 v60, v60
	v_exp_f32_e32 v61, v61
	v_fma_f32 v0, v0, s49, 0.5
	v_fma_f32 v59, v59, s49, 0.5
	v_add_f32_e32 v60, 1.0, v60
	v_max_f32_e32 v0, 1.0, v0
	v_max_f32_e32 v59, 1.0, v59
	v_add_f32_e32 v61, 1.0, v61
	v_cvt_u32_f32_e32 v0, v0
	v_cvt_u32_f32_e32 v59, v59
	v_rcp_f32_e32 v60, v60
	v_rcp_f32_e32 v61, v61
	v_mul_f32_e32 v54, 0xba38aa3b, v54
	v_lshl_or_b32 v0, v59, 8, v0
	v_fma_f32 v59, v60, s49, 0.5
	v_fma_f32 v60, v61, s49, 0.5
	v_max_f32_e32 v59, 1.0, v59
	v_max_f32_e32 v60, 1.0, v60
	v_mul_f32_e32 v55, 0xba38aa3b, v55
	v_cvt_u32_f32_sdwa v59, v59 dst_sel:WORD_1 dst_unused:UNUSED_PAD src0_sel:DWORD
	v_cvt_u32_f32_sdwa v60, v60 dst_sel:BYTE_3 dst_unused:UNUSED_PAD src0_sel:DWORD
	v_exp_f32_e32 v54, v54
	v_exp_f32_e32 v55, v55
	v_mul_f32_e32 v50, 0xba38aa3b, v50
	v_or3_b32 v59, v0, v59, v60
	v_add_f32_e32 v0, 1.0, v54
	v_add_f32_e32 v54, 1.0, v55
	v_mul_f32_e32 v55, 0xba38aa3b, v56
	v_mul_f32_e32 v56, 0xba38aa3b, v57
	v_mul_f32_e32 v51, 0xba38aa3b, v51
	v_exp_f32_e32 v55, v55
	v_exp_f32_e32 v56, v56
	v_exp_f32_e32 v50, v50
	v_exp_f32_e32 v51, v51
	v_mul_f32_e32 v52, 0xba38aa3b, v52
	v_mul_f32_e32 v53, 0xba38aa3b, v53
	v_exp_f32_e32 v52, v52
	v_exp_f32_e32 v53, v53
	v_rcp_f32_e32 v0, v0
	v_rcp_f32_e32 v54, v54
	v_add_f32_e32 v55, 1.0, v55
	v_add_f32_e32 v56, 1.0, v56
	v_add_f32_e32 v50, 1.0, v50
	v_add_f32_e32 v51, 1.0, v51
	v_rcp_f32_e32 v55, v55
	v_rcp_f32_e32 v56, v56
	v_rcp_f32_e32 v50, v50
	v_rcp_f32_e32 v51, v51
	v_add_f32_e32 v52, 1.0, v52
	v_add_f32_e32 v53, 1.0, v53
	v_rcp_f32_e32 v52, v52
	v_rcp_f32_e32 v53, v53
	v_fma_f32 v0, v0, s49, 0.5
	v_fma_f32 v54, v54, s49, 0.5
	v_max_f32_e32 v0, 1.0, v0
	v_max_f32_e32 v54, 1.0, v54
	v_fma_f32 v55, v55, s49, 0.5
	v_fma_f32 v56, v56, s49, 0.5
; #define GAS __attribute__((address_space(1)))
; __device__ __forceinline__ unsigned gate_q8(float g) { return (unsigned)fmaxf(g * 255.0f + 0.5f, 1.0f); }
; __device__ __forceinline__ unsigned gate_pk4(const f32x4& g) { return gate_q8(g[0]) | (gate_q8(g[1]) << 8) | (gate_q8(g[2]) << 16) | (gate_q8(g[3]) << 24); }
;     __device__ __forceinline__ void operator()(const f32x4 (&acc)[2][2][4][2], const pg8::GUnit& u, int wr, int wc, int fr, int fq) const {
;     ...
;         for (int ai = 0; ai < 2; ++ai)
; #pragma unroll
;             for (int m = 0; m < 4; ++m) { u32x4 w; unsigned wq[4];
; #pragma unroll
;                 for (int bj = 0; bj < 2; ++bj)
; #pragma unroll
;                     for (int n = 0; n < 2; ++n) { f32x4 v = acc[ai][bj][m][n];
; #pragma unroll
;                         for (int j = 0; j < 4; ++j) v[j] = __builtin_amdgcn_rcpf(1.0f + __builtin_amdgcn_exp2f(v[j] * (-LOG2E * G8_DESCALE)));
;                         wq[bj * 2 + n] = gate_pk4(v); }
;                 w.x = wq[0]; w.y = wq[1]; w.z = wq[2]; w.w = wq[3];
;                 *(GAS u32x4*)(gb + (size_t)((ai * 4 + m) * 4) * (INW * 2)) = w; }
	v_fma_f32 v50, v50, s49, 0.5
	v_fma_f32 v51, v51, s49, 0.5
	v_cvt_u32_f32_e32 v0, v0
	v_cvt_u32_f32_e32 v54, v54
	v_max_f32_e32 v55, 1.0, v55
	v_max_f32_e32 v56, 1.0, v56
	v_max_f32_e32 v50, 1.0, v50
	v_max_f32_e32 v51, 1.0, v51
	v_fma_f32 v52, v52, s49, 0.5
	v_fma_f32 v53, v53, s49, 0.5
	v_cvt_u32_f32_sdwa v55, v55 dst_sel:WORD_1 dst_unused:UNUSED_PAD src0_sel:DWORD
	v_cvt_u32_f32_sdwa v56, v56 dst_sel:BYTE_3 dst_unused:UNUSED_PAD src0_sel:DWORD
	v_cvt_u32_f32_e32 v50, v50
	v_cvt_u32_f32_e32 v51, v51
	v_max_f32_e32 v52, 1.0, v52
	v_max_f32_e32 v53, 1.0, v53
	v_cvt_u32_f32_sdwa v52, v52 dst_sel:WORD_1 dst_unused:UNUSED_PAD src0_sel:DWORD
	v_cvt_u32_f32_sdwa v53, v53 dst_sel:BYTE_3 dst_unused:UNUSED_PAD src0_sel:DWORD
	v_lshl_or_b32 v0, v54, 8, v0
	v_or3_b32 v60, v0, v55, v56
	v_lshl_or_b32 v0, v51, 8, v50
	v_or3_b32 v61, v0, v52, v53
	v_mul_f32_e32 v0, 0xba38aa3b, v46
	v_mul_f32_e32 v46, 0xba38aa3b, v47
	v_exp_f32_e32 v0, v0
	v_exp_f32_e32 v50, v46
	v_mul_f32_e32 v48, 0xba38aa3b, v48
	v_mul_f32_e32 v49, 0xba38aa3b, v49
	v_exp_f32_e32 v48, v48
	v_exp_f32_e32 v49, v49
	v_add_f32_e32 v0, 1.0, v0
	v_add_f32_e32 v50, 1.0, v50
	v_rcp_f32_e32 v0, v0
	v_rcp_f32_e32 v50, v50
	v_add_f32_e32 v48, 1.0, v48
	v_add_f32_e32 v49, 1.0, v49
	v_rcp_f32_e32 v48, v48
	v_rcp_f32_e32 v49, v49
	v_fma_f32 v0, v0, s49, 0.5
	v_fma_f32 v50, v50, s49, 0.5
	v_max_f32_e32 v0, 1.0, v0
	v_max_f32_e32 v50, 1.0, v50
	v_fma_f32 v48, v48, s49, 0.5
	v_fma_f32 v49, v49, s49, 0.5
	v_cvt_u32_f32_e32 v0, v0
	v_cvt_u32_f32_e32 v50, v50
	v_max_f32_e32 v48, 1.0, v48
	v_max_f32_e32 v49, 1.0, v49
	v_mul_f32_e32 v42, 0xba38aa3b, v42
	v_mul_f32_e32 v43, 0xba38aa3b, v43
	v_cvt_u32_f32_sdwa v48, v48 dst_sel:WORD_1 dst_unused:UNUSED_PAD src0_sel:DWORD
	v_cvt_u32_f32_sdwa v49, v49 dst_sel:BYTE_3 dst_unused:UNUSED_PAD src0_sel:DWORD
	v_exp_f32_e32 v51, v42
	v_exp_f32_e32 v43, v43
	v_lshl_or_b32 v0, v50, 8, v0
	v_or3_b32 v42, v0, v48, v49
	v_add_f32_e32 v0, 1.0, v51
	v_add_f32_e32 v43, 1.0, v43
	v_mul_f32_e32 v44, 0xba38aa3b, v44
	v_rcp_f32_e32 v0, v0
	v_rcp_f32_e32 v43, v43
	v_mul_f32_e32 v45, 0xba38aa3b, v45
	v_exp_f32_e32 v44, v44
	v_exp_f32_e32 v45, v45
	v_fma_f32 v0, v0, s49, 0.5
	v_fma_f32 v43, v43, s49, 0.5
	v_add_f32_e32 v44, 1.0, v44
	v_max_f32_e32 v0, 1.0, v0
	v_max_f32_e32 v43, 1.0, v43
	v_add_f32_e32 v45, 1.0, v45
	v_cvt_u32_f32_e32 v0, v0
	v_cvt_u32_f32_e32 v43, v43
	v_rcp_f32_e32 v44, v44
	v_rcp_f32_e32 v45, v45
	v_mul_f32_e32 v38, 0xba38aa3b, v38
	v_lshl_or_b32 v0, v43, 8, v0
	v_fma_f32 v43, v44, s49, 0.5
	v_fma_f32 v44, v45, s49, 0.5
	v_max_f32_e32 v43, 1.0, v43
	v_max_f32_e32 v44, 1.0, v44
	v_mul_f32_e32 v39, 0xba38aa3b, v39
	v_cvt_u32_f32_sdwa v43, v43 dst_sel:WORD_1 dst_unused:UNUSED_PAD src0_sel:DWORD
	v_cvt_u32_f32_sdwa v44, v44 dst_sel:BYTE_3 dst_unused:UNUSED_PAD src0_sel:DWORD
	v_exp_f32_e32 v38, v38
	v_exp_f32_e32 v39, v39
	v_mul_f32_e32 v34, 0xba38aa3b, v34
	v_or3_b32 v43, v0, v43, v44
	v_add_f32_e32 v0, 1.0, v38
	v_add_f32_e32 v38, 1.0, v39
	v_mul_f32_e32 v39, 0xba38aa3b, v40
	v_mul_f32_e32 v40, 0xba38aa3b, v41
	v_mul_f32_e32 v35, 0xba38aa3b, v35
	v_exp_f32_e32 v39, v39
	v_exp_f32_e32 v40, v40
	v_exp_f32_e32 v34, v34
	v_exp_f32_e32 v35, v35
	v_mul_f32_e32 v36, 0xba38aa3b, v36
	v_mul_f32_e32 v37, 0xba38aa3b, v37
	v_exp_f32_e32 v36, v36
	v_exp_f32_e32 v37, v37
	v_rcp_f32_e32 v0, v0
	v_rcp_f32_e32 v38, v38
	v_add_f32_e32 v39, 1.0, v39
	v_add_f32_e32 v40, 1.0, v40
	v_add_f32_e32 v34, 1.0, v34
	v_add_f32_e32 v35, 1.0, v35
	v_rcp_f32_e32 v39, v39
	v_rcp_f32_e32 v40, v40
	v_rcp_f32_e32 v34, v34
	v_rcp_f32_e32 v35, v35
	v_add_f32_e32 v36, 1.0, v36
	v_add_f32_e32 v37, 1.0, v37
	v_rcp_f32_e32 v36, v36
	v_rcp_f32_e32 v37, v37
	v_fma_f32 v0, v0, s49, 0.5
	v_fma_f32 v38, v38, s49, 0.5
	v_max_f32_e32 v0, 1.0, v0
	v_max_f32_e32 v38, 1.0, v38
	v_fma_f32 v39, v39, s49, 0.5
	v_fma_f32 v40, v40, s49, 0.5
	v_fma_f32 v34, v34, s49, 0.5
	v_fma_f32 v35, v35, s49, 0.5
	v_cvt_u32_f32_e32 v0, v0
	v_cvt_u32_f32_e32 v38, v38
	v_max_f32_e32 v39, 1.0, v39
	v_max_f32_e32 v40, 1.0, v40
	v_max_f32_e32 v34, 1.0, v34
	v_max_f32_e32 v35, 1.0, v35
	v_fma_f32 v36, v36, s49, 0.5
	v_fma_f32 v37, v37, s49, 0.5
	v_cvt_u32_f32_sdwa v39, v39 dst_sel:WORD_1 dst_unused:UNUSED_PAD src0_sel:DWORD
	v_cvt_u32_f32_sdwa v40, v40 dst_sel:BYTE_3 dst_unused:UNUSED_PAD src0_sel:DWORD
	v_cvt_u32_f32_e32 v34, v34
	v_cvt_u32_f32_e32 v35, v35
	v_max_f32_e32 v36, 1.0, v36
	v_max_f32_e32 v37, 1.0, v37
	v_cvt_u32_f32_sdwa v36, v36 dst_sel:WORD_1 dst_unused:UNUSED_PAD src0_sel:DWORD
	v_cvt_u32_f32_sdwa v37, v37 dst_sel:BYTE_3 dst_unused:UNUSED_PAD src0_sel:DWORD
	v_lshl_or_b32 v0, v38, 8, v0
	v_or3_b32 v44, v0, v39, v40
	v_lshl_or_b32 v0, v35, 8, v34
	v_or3_b32 v45, v0, v36, v37
	v_mul_f32_e32 v0, 0xba38aa3b, v30
	v_mul_f32_e32 v30, 0xba38aa3b, v31
	v_exp_f32_e32 v0, v0
	v_exp_f32_e32 v34, v30
	v_mul_f32_e32 v32, 0xba38aa3b, v32
	v_mul_f32_e32 v33, 0xba38aa3b, v33
	v_exp_f32_e32 v32, v32
	v_exp_f32_e32 v33, v33
	v_add_f32_e32 v0, 1.0, v0
	v_add_f32_e32 v34, 1.0, v34
	v_rcp_f32_e32 v0, v0
	v_rcp_f32_e32 v34, v34
	v_add_f32_e32 v32, 1.0, v32
	v_add_f32_e32 v33, 1.0, v33
	v_rcp_f32_e32 v32, v32
	v_rcp_f32_e32 v33, v33
	v_fma_f32 v0, v0, s49, 0.5
	v_fma_f32 v34, v34, s49, 0.5
	v_max_f32_e32 v0, 1.0, v0
	v_max_f32_e32 v34, 1.0, v34
	v_fma_f32 v32, v32, s49, 0.5
	v_fma_f32 v33, v33, s49, 0.5
	v_cvt_u32_f32_e32 v0, v0
	v_cvt_u32_f32_e32 v34, v34
	v_max_f32_e32 v32, 1.0, v32
	v_max_f32_e32 v33, 1.0, v33
	v_mul_f32_e32 v26, 0xba38aa3b, v26
	v_mul_f32_e32 v27, 0xba38aa3b, v27
	v_cvt_u32_f32_sdwa v32, v32 dst_sel:WORD_1 dst_unused:UNUSED_PAD src0_sel:DWORD
	v_cvt_u32_f32_sdwa v33, v33 dst_sel:BYTE_3 dst_unused:UNUSED_PAD src0_sel:DWORD
; #define GAS __attribute__((address_space(1)))
; __device__ __forceinline__ unsigned gate_q8(float g) { return (unsigned)fmaxf(g * 255.0f + 0.5f, 1.0f); }
; __device__ __forceinline__ unsigned gate_pk4(const f32x4& g) { return gate_q8(g[0]) | (gate_q8(g[1]) << 8) | (gate_q8(g[2]) << 16) | (gate_q8(g[3]) << 24); }
;     __device__ __forceinline__ void operator()(const f32x4 (&acc)[2][2][4][2], const pg8::GUnit& u, int wr, int wc, int fr, int fq) const {
;     ...
;         for (int ai = 0; ai < 2; ++ai)
; #pragma unroll
;             for (int m = 0; m < 4; ++m) { u32x4 w; unsigned wq[4];
; #pragma unroll
;                 for (int bj = 0; bj < 2; ++bj)
; #pragma unroll
;                     for (int n = 0; n < 2; ++n) { f32x4 v = acc[ai][bj][m][n];
; #pragma unroll
;                         for (int j = 0; j < 4; ++j) v[j] = __builtin_amdgcn_rcpf(1.0f + __builtin_amdgcn_exp2f(v[j] * (-LOG2E * G8_DESCALE)));
;                         wq[bj * 2 + n] = gate_pk4(v); }
;                 w.x = wq[0]; w.y = wq[1]; w.z = wq[2]; w.w = wq[3];
;                 *(GAS u32x4*)(gb + (size_t)((ai * 4 + m) * 4) * (INW * 2)) = w; }
	v_exp_f32_e32 v35, v26
	v_exp_f32_e32 v27, v27
	v_lshl_or_b32 v0, v34, 8, v0
	v_or3_b32 v26, v0, v32, v33
	v_add_f32_e32 v0, 1.0, v35
	v_add_f32_e32 v27, 1.0, v27
	v_mul_f32_e32 v28, 0xba38aa3b, v28
	v_rcp_f32_e32 v0, v0
	v_rcp_f32_e32 v27, v27
	v_mul_f32_e32 v29, 0xba38aa3b, v29
	v_exp_f32_e32 v28, v28
	v_exp_f32_e32 v29, v29
	v_fma_f32 v0, v0, s49, 0.5
	v_fma_f32 v27, v27, s49, 0.5
	v_add_f32_e32 v28, 1.0, v28
	v_max_f32_e32 v0, 1.0, v0
	v_max_f32_e32 v27, 1.0, v27
	v_add_f32_e32 v29, 1.0, v29
	v_cvt_u32_f32_e32 v0, v0
	v_cvt_u32_f32_e32 v27, v27
	v_rcp_f32_e32 v28, v28
	v_rcp_f32_e32 v29, v29
	v_mul_f32_e32 v22, 0xba38aa3b, v22
	v_lshl_or_b32 v0, v27, 8, v0
	v_fma_f32 v27, v28, s49, 0.5
	v_fma_f32 v28, v29, s49, 0.5
	v_max_f32_e32 v27, 1.0, v27
	v_max_f32_e32 v28, 1.0, v28
	v_mul_f32_e32 v23, 0xba38aa3b, v23
	v_cvt_u32_f32_sdwa v27, v27 dst_sel:WORD_1 dst_unused:UNUSED_PAD src0_sel:DWORD
	v_cvt_u32_f32_sdwa v28, v28 dst_sel:BYTE_3 dst_unused:UNUSED_PAD src0_sel:DWORD
	v_exp_f32_e32 v22, v22
	v_exp_f32_e32 v23, v23
	v_mul_f32_e32 v18, 0xba38aa3b, v18
	v_or3_b32 v27, v0, v27, v28
	v_add_f32_e32 v0, 1.0, v22
	v_add_f32_e32 v22, 1.0, v23
	v_mul_f32_e32 v23, 0xba38aa3b, v24
	v_mul_f32_e32 v24, 0xba38aa3b, v25
	v_mul_f32_e32 v19, 0xba38aa3b, v19
	v_exp_f32_e32 v23, v23
	v_exp_f32_e32 v24, v24
	v_exp_f32_e32 v18, v18
	v_exp_f32_e32 v19, v19
	v_mul_f32_e32 v20, 0xba38aa3b, v20
	v_mul_f32_e32 v21, 0xba38aa3b, v21
	v_exp_f32_e32 v20, v20
	v_exp_f32_e32 v21, v21
	v_rcp_f32_e32 v0, v0
	v_rcp_f32_e32 v22, v22
	v_add_f32_e32 v23, 1.0, v23
	v_add_f32_e32 v24, 1.0, v24
	v_add_f32_e32 v18, 1.0, v18
	v_add_f32_e32 v19, 1.0, v19
	v_rcp_f32_e32 v23, v23
	v_rcp_f32_e32 v24, v24
	v_rcp_f32_e32 v18, v18
	v_rcp_f32_e32 v19, v19
	v_add_f32_e32 v20, 1.0, v20
	v_add_f32_e32 v21, 1.0, v21
	v_rcp_f32_e32 v20, v20
	v_rcp_f32_e32 v21, v21
	v_fma_f32 v0, v0, s49, 0.5
	v_fma_f32 v22, v22, s49, 0.5
	v_max_f32_e32 v0, 1.0, v0
	v_max_f32_e32 v22, 1.0, v22
	v_fma_f32 v23, v23, s49, 0.5
	v_fma_f32 v24, v24, s49, 0.5
	v_fma_f32 v18, v18, s49, 0.5
	v_fma_f32 v19, v19, s49, 0.5
	v_cvt_u32_f32_e32 v0, v0
	v_cvt_u32_f32_e32 v22, v22
	v_max_f32_e32 v23, 1.0, v23
	v_max_f32_e32 v24, 1.0, v24
	v_max_f32_e32 v18, 1.0, v18
	v_max_f32_e32 v19, 1.0, v19
	v_fma_f32 v20, v20, s49, 0.5
	v_fma_f32 v21, v21, s49, 0.5
	v_cvt_u32_f32_sdwa v23, v23 dst_sel:WORD_1 dst_unused:UNUSED_PAD src0_sel:DWORD
	v_cvt_u32_f32_sdwa v24, v24 dst_sel:BYTE_3 dst_unused:UNUSED_PAD src0_sel:DWORD
	v_cvt_u32_f32_e32 v18, v18
	v_cvt_u32_f32_e32 v19, v19
	v_max_f32_e32 v20, 1.0, v20
	v_max_f32_e32 v21, 1.0, v21
	v_cvt_u32_f32_sdwa v20, v20 dst_sel:WORD_1 dst_unused:UNUSED_PAD src0_sel:DWORD
	v_cvt_u32_f32_sdwa v21, v21 dst_sel:BYTE_3 dst_unused:UNUSED_PAD src0_sel:DWORD
	v_lshl_or_b32 v0, v22, 8, v0
	v_or3_b32 v28, v0, v23, v24
	v_lshl_or_b32 v0, v19, 8, v18
	v_or3_b32 v29, v0, v20, v21
	v_mul_f32_e32 v0, 0xba38aa3b, v14
	v_mul_f32_e32 v14, 0xba38aa3b, v15
	v_exp_f32_e32 v0, v0
	v_exp_f32_e32 v18, v14
	v_mul_f32_e32 v16, 0xba38aa3b, v16
	v_mul_f32_e32 v17, 0xba38aa3b, v17
	v_exp_f32_e32 v16, v16
	v_exp_f32_e32 v17, v17
	v_add_f32_e32 v0, 1.0, v0
	v_add_f32_e32 v18, 1.0, v18
	v_rcp_f32_e32 v0, v0
	v_rcp_f32_e32 v18, v18
	v_add_f32_e32 v16, 1.0, v16
	v_add_f32_e32 v17, 1.0, v17
	v_rcp_f32_e32 v16, v16
	v_rcp_f32_e32 v17, v17
	v_fma_f32 v0, v0, s49, 0.5
	v_fma_f32 v18, v18, s49, 0.5
	v_max_f32_e32 v0, 1.0, v0
	v_max_f32_e32 v18, 1.0, v18
	v_fma_f32 v16, v16, s49, 0.5
	v_fma_f32 v17, v17, s49, 0.5
	v_cvt_u32_f32_e32 v0, v0
	v_cvt_u32_f32_e32 v18, v18
	v_max_f32_e32 v16, 1.0, v16
	v_max_f32_e32 v17, 1.0, v17
	v_mul_f32_e32 v10, 0xba38aa3b, v10
	v_mul_f32_e32 v11, 0xba38aa3b, v11
	v_cvt_u32_f32_sdwa v16, v16 dst_sel:WORD_1 dst_unused:UNUSED_PAD src0_sel:DWORD
	v_cvt_u32_f32_sdwa v17, v17 dst_sel:BYTE_3 dst_unused:UNUSED_PAD src0_sel:DWORD
	v_exp_f32_e32 v19, v10
	v_exp_f32_e32 v11, v11
	v_lshl_or_b32 v0, v18, 8, v0
	v_or3_b32 v10, v0, v16, v17
	v_add_f32_e32 v0, 1.0, v19
	v_add_f32_e32 v11, 1.0, v11
	v_mul_f32_e32 v12, 0xba38aa3b, v12
	v_rcp_f32_e32 v0, v0
; #define GAS __attribute__((address_space(1)))
; __device__ __forceinline__ unsigned gate_pk4(const f32x4& g) { return gate_q8(g[0]) | (gate_q8(g[1]) << 8) | (gate_q8(g[2]) << 16) | (gate_q8(g[3]) << 24); }
; #define PG8_WAIT_V(n) asm volatile("s_waitcnt vmcnt(" #n ")" ::: "memory")
; #define PG8_BAR __builtin_amdgcn_s_barrier()
;     ...
;         if (!has_next) break;
; #pragma unroll
;         for (int a = 0; a < 2; ++a)
; #pragma unroll
;             for (int b = 0; b < 2; ++b)
; #pragma unroll
;                 for (int m = 0; m < 4; ++m)
; #pragma unroll
;                     for (int n = 0; n < 2; ++n) acc[a][b][m][n] = (f32x4){0.f, 0.f, 0.f, 0.f};
;         cur = nxt; cA = nA; cB = nB; ++ui;
;     }
;     PG8_WAIT_V(0);
;     if (wr == 0) PG8_BAR;
;     PG8_BAR;
;     __device__ __forceinline__ void operator()(const f32x4 (&acc)[2][2][4][2], const pg8::GUnit& u, int wr, int wc, int fr, int fq) const {
;     ...
;         GAS unsigned char* gb = (GAS unsigned char*)P + (size_t)(u.pm * 256 + (wr * 4 + wc) * 32 + fq) * (INW * 2) + (GA * 2 + u.pn * 256 + fr * 16);
; #pragma unroll
;         for (int ai = 0; ai < 2; ++ai)
; #pragma unroll
;             for (int m = 0; m < 4; ++m) { u32x4 w; unsigned wq[4];
; #pragma unroll
;                 for (int bj = 0; bj < 2; ++bj)
; #pragma unroll
;                     for (int n = 0; n < 2; ++n) { f32x4 v = acc[ai][bj][m][n];
; #pragma unroll
;                         for (int j = 0; j < 4; ++j) v[j] = __builtin_amdgcn_rcpf(1.0f + __builtin_amdgcn_exp2f(v[j] * (-LOG2E * G8_DESCALE)));
;                         wq[bj * 2 + n] = gate_pk4(v); }
;                 w.x = wq[0]; w.y = wq[1]; w.z = wq[2]; w.w = wq[3];
;                 *(GAS u32x4*)(gb + (size_t)((ai * 4 + m) * 4) * (INW * 2)) = w; }
	v_rcp_f32_e32 v11, v11
	v_mul_f32_e32 v13, 0xba38aa3b, v13
	v_exp_f32_e32 v12, v12
	v_exp_f32_e32 v13, v13
	v_fma_f32 v0, v0, s49, 0.5
	v_fma_f32 v11, v11, s49, 0.5
	v_add_f32_e32 v12, 1.0, v12
	v_max_f32_e32 v0, 1.0, v0
	v_max_f32_e32 v11, 1.0, v11
	v_add_f32_e32 v13, 1.0, v13
	v_cvt_u32_f32_e32 v0, v0
	v_cvt_u32_f32_e32 v11, v11
	v_rcp_f32_e32 v12, v12
	v_rcp_f32_e32 v13, v13
	v_mul_f32_e32 v6, 0xba38aa3b, v6
	v_lshl_or_b32 v0, v11, 8, v0
	v_fma_f32 v11, v12, s49, 0.5
	v_fma_f32 v12, v13, s49, 0.5
	v_max_f32_e32 v11, 1.0, v11
	v_max_f32_e32 v12, 1.0, v12
	v_mul_f32_e32 v7, 0xba38aa3b, v7
	v_cvt_u32_f32_sdwa v11, v11 dst_sel:WORD_1 dst_unused:UNUSED_PAD src0_sel:DWORD
	v_cvt_u32_f32_sdwa v12, v12 dst_sel:BYTE_3 dst_unused:UNUSED_PAD src0_sel:DWORD
	v_exp_f32_e32 v6, v6
	v_exp_f32_e32 v7, v7
	s_lshl_b32 s39, s39, 8
	s_add_i32 s39, s40, s39
	v_or3_b32 v11, v0, v11, v12
	v_add_f32_e32 v0, 1.0, v6
	v_add_f32_e32 v6, 1.0, v7
	v_mul_f32_e32 v7, 0xba38aa3b, v8
	v_mul_f32_e32 v8, 0xba38aa3b, v9
	v_mul_f32_e32 v2, 0xba38aa3b, v2
	v_mul_f32_e32 v3, 0xba38aa3b, v3
	v_add_u32_e32 v140, s39, v140
	v_exp_f32_e32 v7, v7
	v_exp_f32_e32 v8, v8
	v_exp_f32_e32 v2, v2
	v_exp_f32_e32 v3, v3
	v_mad_i64_i32 v[140:141], s[44:45], v140, s93, v[132:133]
	v_ashrrev_i32_e32 v143, 31, v142
	v_mul_f32_e32 v4, 0xba38aa3b, v4
	v_mul_f32_e32 v5, 0xba38aa3b, v5
	v_lshl_add_u64 v[126:127], v[140:141], 0, v[142:143]
	v_exp_f32_e32 v4, v4
	v_exp_f32_e32 v5, v5
	v_add_co_u32_e32 v94, vcc, s48, v126
	v_rcp_f32_e32 v0, v0
	s_nop 0
	v_addc_co_u32_e32 v95, vcc, 0, v127, vcc
	v_rcp_f32_e32 v6, v6
	v_add_f32_e32 v7, 1.0, v7
	v_add_f32_e32 v8, 1.0, v8
	v_add_f32_e32 v2, 1.0, v2
	v_add_f32_e32 v3, 1.0, v3
	v_add_co_u32_e32 v78, vcc, s26, v126
	v_rcp_f32_e32 v7, v7
	v_rcp_f32_e32 v8, v8
	v_rcp_f32_e32 v2, v2
	v_rcp_f32_e32 v3, v3
	v_addc_co_u32_e32 v79, vcc, 0, v127, vcc
	s_mov_b32 s38, 0x90000
	v_add_f32_e32 v4, 1.0, v4
	v_add_f32_e32 v5, 1.0, v5
	v_add_co_u32_e32 v62, vcc, s38, v126
	v_rcp_f32_e32 v4, v4
	v_rcp_f32_e32 v5, v5
	v_addc_co_u32_e32 v63, vcc, 0, v127, vcc
	s_mov_b32 s38, 0xc0000
	v_fma_f32 v0, v0, s49, 0.5
	v_fma_f32 v6, v6, s49, 0.5
	v_add_co_u32_e32 v46, vcc, s38, v126
	v_max_f32_e32 v0, 1.0, v0
	v_max_f32_e32 v6, 1.0, v6
	v_fma_f32 v7, v7, s49, 0.5
	v_fma_f32 v8, v8, s49, 0.5
	v_fma_f32 v2, v2, s49, 0.5
	v_fma_f32 v3, v3, s49, 0.5
	v_addc_co_u32_e32 v47, vcc, 0, v127, vcc
	s_mov_b32 s38, 0xf0000
	v_cvt_u32_f32_e32 v0, v0
	v_cvt_u32_f32_e32 v6, v6
	v_max_f32_e32 v7, 1.0, v7
	v_max_f32_e32 v8, 1.0, v8
	v_max_f32_e32 v2, 1.0, v2
	v_max_f32_e32 v3, 1.0, v3
	v_add_co_u32_e32 v30, vcc, s38, v126
	v_cvt_u32_f32_sdwa v7, v7 dst_sel:WORD_1 dst_unused:UNUSED_PAD src0_sel:DWORD
	v_cvt_u32_f32_sdwa v8, v8 dst_sel:BYTE_3 dst_unused:UNUSED_PAD src0_sel:DWORD
	v_cvt_u32_f32_e32 v2, v2
	v_cvt_u32_f32_e32 v3, v3
	v_fma_f32 v4, v4, s49, 0.5
	v_fma_f32 v5, v5, s49, 0.5
	v_addc_co_u32_e32 v31, vcc, 0, v127, vcc
	v_max_f32_e32 v4, 1.0, v4
	v_max_f32_e32 v5, 1.0, v5
	v_add_co_u32_e32 v14, vcc, s27, v126
	v_cvt_u32_f32_sdwa v4, v4 dst_sel:WORD_1 dst_unused:UNUSED_PAD src0_sel:DWORD
	v_cvt_u32_f32_sdwa v5, v5 dst_sel:BYTE_3 dst_unused:UNUSED_PAD src0_sel:DWORD
	v_addc_co_u32_e32 v15, vcc, 0, v127, vcc
	v_lshl_or_b32 v0, v6, 8, v0
	v_or3_b32 v12, v0, v7, v8
	v_lshl_or_b32 v0, v3, 8, v2
	v_add_co_u32_e32 v2, vcc, 0x150000, v126
	v_or3_b32 v13, v0, v4, v5
	s_nop 0
	v_addc_co_u32_e32 v3, vcc, 0, v127, vcc
	s_and_b64 vcc, exec, s[4:5]
	s_mov_b32 s39, s25
	s_mov_b32 s38, s24
	s_mov_b32 s45, s37
	s_mov_b32 s44, s36
	global_store_dwordx4 v[126:127], v[122:125], off
	global_store_dwordx4 v[94:95], v[106:109], off
	global_store_dwordx4 v[78:79], v[90:93], off
	global_store_dwordx4 v[62:63], v[74:77], off
	global_store_dwordx4 v[46:47], v[58:61], off
	global_store_dwordx4 v[30:31], v[42:45], off
	global_store_dwordx4 v[14:15], v[26:29], off
	global_store_dwordx4 v[2:3], v[10:13], off
	s_cbranch_vccz .LBB0_556
	v_readlane_b32 s4, v255, 6
	s_waitcnt vmcnt(0)
	v_readlane_b32 s5, v255, 7
	s_andn2_b64 vcc, exec, s[4:5]
	s_cbranch_vccnz .LBB0_563
	s_barrier

; __device__ __forceinline__ int lane_id_hw() { int l; asm volatile("v_mbcnt_lo_u32_b32 %0, -1, 0\n\tv_mbcnt_hi_u32_b32 %0, -1, %0" : "=v"(l)); return l; }
; #define PG8_STAGE(bufoff, gbase, voff) do { unsigned _g = (gbase); asm volatile("" : "+s"(_g));   _Pragma("unroll") for (int _i = 0; _i < 2; ++_i) \
;         __builtin_amdgcn_global_load_lds((const unsigned*)(wsb + (size_t)(unsigned)(_g + (voff)[_i])), (LAS unsigned*)(lds + (bufoff) + ldsw + _i * 8192), 16, 0, 0); } while (0)
; #define PG8_WAIT_V(n) asm volatile("s_waitcnt vmcnt(" #n ")" ::: "memory")
; #define PG8_WAIT_L(n) asm volatile("s_waitcnt lgkmcnt(" #n ")" ::: "memory")
; #define PG8_BAR __builtin_amdgcn_s_barrier()
; #define PG8_SCHED __builtin_amdgcn_sched_barrier(0)
;     ...
;         for (int t = 0; t < nt; t += 2) {
;             if constexpr (Epi::HAS_MID) { if (t == Epi::MID0 || t == Epi::MID1) { const int l2 = lane_id_hw(); E.mid(acc, cur, t == Epi::MID0 ? 0 : 1, wr, wc, l2 & 15, l2 >> 4); } }
;             const bool last = (t == nt - 2);
;             const unsigned a1 = cA + (unsigned)(t + 1) * kstep;
;             const unsigned a2 = last ? nA : cA + (unsigned)(t + 2) * kstep, b2 = last ? nB : cB + (unsigned)(t + 2) * kstep;
;             const unsigned a3 = a2 + kstep, b3 = b2 + kstep;
;             if constexpr (SP2) {
;             PG8_LDB(B0, 0, 0); PG8_LDB(B1, 0, 1); PG8_SCHED; PG8_LDA(At, 0, 0); PG8_STAGE(PG8_SA(1, 1), a1 + hstep, voffA);
;             PG8_WAIT_V(8); PG8_WAIT_L(0); PG8_BAR; PG8_MMA(0, 0, At, B0); PG8_MMA(0, 1, At, B1); PG8_BAR; PG8_SCHED;
;             PG8_LDA(At, 0, 1); PG8_STAGE(PG8_SB(0, 0), b2, voffB); PG8_STAGE(PG8_SB(0, 1), b2 + hstep, voffB); PG8_STAGE(PG8_SA(0, 0), a2, voffA);
;             PG8_WAIT_V(8); PG8_WAIT_L(0); PG8_BAR; PG8_MMA(1, 0, At, B0); PG8_MMA(1, 1, At, B1); PG8_BAR; PG8_SCHED;
;             PG8_LDB(B0, 1, 0); PG8_LDB(B1, 1, 1); PG8_SCHED; PG8_LDA(At, 1, 0); PG8_STAGE(PG8_SA(0, 1), a2 + hstep, voffA);
;             PG8_WAIT_V(8); PG8_WAIT_L(0); PG8_BAR; PG8_MMA(0, 0, At, B0); PG8_MMA(0, 1, At, B1); PG8_BAR; PG8_SCHED;
.Lprio_skip_2:
.LBB0_862:
	v_readfirstlane_b32 s100, v130
	v_readfirstlane_b32 s101, v131
	s_nop 1
	s_sub_u32 s100, s100, 0x10000000
	s_subb_u32 s101, s101, 0
	s_add_i32 s47, s10, 0xfff00080
	s_cmp_eq_u32 s18, 60
	s_cselect_b32 s83, s45, s47
	s_cselect_b32 s82, s46, s11
	s_add_i32 s84, 0, 0x10000
	s_waitcnt lgkmcnt(0)
	v_add_u32_e32 v0, s84, v144
	s_add_i32 s86, 0, 0x14000
	ds_read_b128 v[136:139], v0
	ds_read_b128 v[146:149], v0 offset:1024
	ds_read_b128 v[150:153], v0 offset:2048
	ds_read_b128 v[154:157], v0 offset:3072
	v_add_u32_e32 v0, s86, v144
	ds_read_b128 v[158:161], v0
	ds_read_b128 v[162:165], v0 offset:1024
	ds_read_b128 v[166:169], v0 offset:2048
	ds_read_b128 v[170:173], v0 offset:3072
	s_add_i32 s47, s83, 0x80
	s_mov_b32 s87, s10
	ds_read_b128 v[174:177], v145
	ds_read_b128 v[178:181], v145 offset:1024
	ds_read_b128 v[182:185], v145 offset:2048
	ds_read_b128 v[186:189], v145 offset:3072
	ds_read_b128 v[190:193], v145 offset:4096
	ds_read_b128 v[194:197], v145 offset:5120
	ds_read_b128 v[198:201], v145 offset:6144
	ds_read_b128 v[202:205], v145 offset:7168
	s_add_i32 m0, s22, 0xc000
	s_add_i32 vcc_lo, s87, 0x10000000
	s_add_u32 vcc_lo, s100, vcc_lo
	s_addc_u32 vcc_hi, s101, 0
	global_load_lds_dwordx4 v140, vcc
	s_add_i32 m0, s22, 0xe000
	s_nop 0
	global_load_lds_dwordx4 v142, vcc
	s_waitcnt vmcnt(8)
	s_waitcnt lgkmcnt(0)
	s_barrier
	s_waitcnt lgkmcnt(0)
	v_mfma_f32_16x16x32_bf16 v[126:129], v[136:139], v[174:177], v[126:129]
	v_mfma_f32_16x16x32_bf16 v[122:125], v[150:153], v[174:177], v[122:125]
	v_mfma_f32_16x16x32_bf16 v[110:113], v[136:139], v[182:185], v[110:113]
	v_mfma_f32_16x16x32_bf16 v[106:109], v[150:153], v[182:185], v[106:109]
	v_mfma_f32_16x16x32_bf16 v[94:97], v[136:139], v[190:193], v[94:97]
	v_mfma_f32_16x16x32_bf16 v[90:93], v[150:153], v[190:193], v[90:93]
	v_mfma_f32_16x16x32_bf16 v[78:81], v[136:139], v[198:201], v[78:81]
	v_mfma_f32_16x16x32_bf16 v[74:77], v[150:153], v[198:201], v[74:77]
	v_mfma_f32_16x16x32_bf16 v[126:129], v[146:149], v[178:181], v[126:129]
	v_mfma_f32_16x16x32_bf16 v[122:125], v[154:157], v[178:181], v[122:125]
	v_mfma_f32_16x16x32_bf16 v[110:113], v[146:149], v[186:189], v[110:113]
	v_mfma_f32_16x16x32_bf16 v[106:109], v[154:157], v[186:189], v[106:109]
	v_mfma_f32_16x16x32_bf16 v[94:97], v[146:149], v[194:197], v[94:97]
	v_mfma_f32_16x16x32_bf16 v[90:93], v[154:157], v[194:197], v[90:93]
	v_mfma_f32_16x16x32_bf16 v[78:81], v[146:149], v[202:205], v[78:81]
	v_mfma_f32_16x16x32_bf16 v[74:77], v[154:157], v[202:205], v[74:77]
	v_mfma_f32_16x16x32_bf16 v[118:121], v[158:161], v[174:177], v[118:121]
	v_mfma_f32_16x16x32_bf16 v[114:117], v[166:169], v[174:177], v[114:117]
	v_mfma_f32_16x16x32_bf16 v[102:105], v[158:161], v[182:185], v[102:105]
	v_mfma_f32_16x16x32_bf16 v[98:101], v[166:169], v[182:185], v[98:101]
	v_mfma_f32_16x16x32_bf16 v[86:89], v[158:161], v[190:193], v[86:89]
	v_mfma_f32_16x16x32_bf16 v[82:85], v[166:169], v[190:193], v[82:85]
	v_mfma_f32_16x16x32_bf16 v[70:73], v[158:161], v[198:201], v[70:73]
	v_mfma_f32_16x16x32_bf16 v[66:69], v[166:169], v[198:201], v[66:69]
	v_mfma_f32_16x16x32_bf16 v[118:121], v[162:165], v[178:181], v[118:121]
	v_mfma_f32_16x16x32_bf16 v[114:117], v[170:173], v[178:181], v[114:117]
	v_mfma_f32_16x16x32_bf16 v[102:105], v[162:165], v[186:189], v[102:105]
	v_mfma_f32_16x16x32_bf16 v[98:101], v[170:173], v[186:189], v[98:101]
	v_mfma_f32_16x16x32_bf16 v[86:89], v[162:165], v[194:197], v[86:89]
	v_mfma_f32_16x16x32_bf16 v[82:85], v[170:173], v[194:197], v[82:85]
	v_mfma_f32_16x16x32_bf16 v[70:73], v[162:165], v[202:205], v[70:73]
	v_mfma_f32_16x16x32_bf16 v[66:69], v[170:173], v[202:205], v[66:69]
	s_barrier
	s_mov_b32 s87, s82
	ds_read_b128 v[174:177], v145 offset:16384
	ds_read_b128 v[178:181], v145 offset:17408
	ds_read_b128 v[182:185], v145 offset:18432
	ds_read_b128 v[186:189], v145 offset:19456
	ds_read_b128 v[190:193], v145 offset:20480
	ds_read_b128 v[194:197], v145 offset:21504
	ds_read_b128 v[198:201], v145 offset:22528
	ds_read_b128 v[202:205], v145 offset:23552
	s_add_i32 s84, s84, s7
	s_add_i32 vcc_lo, s87, 0x10000000
	s_add_u32 vcc_lo, s100, vcc_lo
	s_addc_u32 vcc_hi, s101, 0
	s_mov_b32 m0, s84
	s_nop 0
	global_load_lds_dwordx4 v141, vcc
	s_add_i32 m0, s84, 0x2000
	s_add_i32 s84, s82, 0x100000
	global_load_lds_dwordx4 v143, vcc
	s_add_i32 s86, s86, s7
	s_add_i32 vcc_lo, s84, 0x10000000
	s_add_u32 vcc_lo, s100, vcc_lo
	s_addc_u32 vcc_hi, s101, 0
	s_mov_b32 m0, s86
	s_nop 0
	global_load_lds_dwordx4 v141, vcc
	s_add_i32 m0, s86, 0x2000
	s_mov_b32 s84, s83
	global_load_lds_dwordx4 v143, vcc
	s_mov_b32 m0, s22
	s_add_i32 vcc_lo, s84, 0x10000000
	s_add_u32 vcc_lo, s100, vcc_lo
	s_addc_u32 vcc_hi, s101, 0
	global_load_lds_dwordx4 v140, vcc
	s_mov_b32 m0, s23
	s_nop 0
	global_load_lds_dwordx4 v142, vcc
	s_waitcnt vmcnt(8)
	s_waitcnt lgkmcnt(0)
	s_barrier
; #define PG8_STAGE(bufoff, gbase, voff) do { unsigned _g = (gbase); asm volatile("" : "+s"(_g));   _Pragma("unroll") for (int _i = 0; _i < 2; ++_i) \
;         __builtin_amdgcn_global_load_lds((const unsigned*)(wsb + (size_t)(unsigned)(_g + (voff)[_i])), (LAS unsigned*)(lds + (bufoff) + ldsw + _i * 8192), 16, 0, 0); } while (0)
; #define PG8_WAIT_V(n) asm volatile("s_waitcnt vmcnt(" #n ")" ::: "memory")
; #define PG8_WAIT_L(n) asm volatile("s_waitcnt lgkmcnt(" #n ")" ::: "memory")
; #define PG8_BAR __builtin_amdgcn_s_barrier()
; #define PG8_SCHED __builtin_amdgcn_sched_barrier(0)
;     ...
;             PG8_WAIT_V(8); PG8_WAIT_L(0); PG8_BAR; PG8_MMA(1, 0, At, B0); PG8_MMA(1, 1, At, B1); PG8_BAR; PG8_SCHED;
;             PG8_LDB(B0, 1, 0); PG8_LDB(B1, 1, 1); PG8_SCHED; PG8_LDA(At, 1, 0); PG8_STAGE(PG8_SA(0, 1), a2 + hstep, voffA);
;             PG8_WAIT_V(8); PG8_WAIT_L(0); PG8_BAR; PG8_MMA(0, 0, At, B0); PG8_MMA(0, 1, At, B1); PG8_BAR; PG8_SCHED;
	s_waitcnt lgkmcnt(0)
	v_mfma_f32_16x16x32_bf16 v[62:65], v[136:139], v[174:177], v[62:65]
	v_mfma_f32_16x16x32_bf16 v[58:61], v[150:153], v[174:177], v[58:61]
	v_mfma_f32_16x16x32_bf16 v[46:49], v[136:139], v[182:185], v[46:49]
	v_mfma_f32_16x16x32_bf16 v[42:45], v[150:153], v[182:185], v[42:45]
	v_mfma_f32_16x16x32_bf16 v[30:33], v[136:139], v[190:193], v[30:33]
	v_mfma_f32_16x16x32_bf16 v[26:29], v[150:153], v[190:193], v[26:29]
	v_mfma_f32_16x16x32_bf16 v[14:17], v[136:139], v[198:201], v[14:17]
	v_mfma_f32_16x16x32_bf16 v[10:13], v[150:153], v[198:201], v[10:13]
	v_mfma_f32_16x16x32_bf16 v[62:65], v[146:149], v[178:181], v[62:65]
	v_mfma_f32_16x16x32_bf16 v[58:61], v[154:157], v[178:181], v[58:61]
	v_mfma_f32_16x16x32_bf16 v[46:49], v[146:149], v[186:189], v[46:49]
	v_mfma_f32_16x16x32_bf16 v[42:45], v[154:157], v[186:189], v[42:45]
	v_mfma_f32_16x16x32_bf16 v[30:33], v[146:149], v[194:197], v[30:33]
	v_mfma_f32_16x16x32_bf16 v[26:29], v[154:157], v[194:197], v[26:29]
	v_mfma_f32_16x16x32_bf16 v[14:17], v[146:149], v[202:205], v[14:17]
	v_mfma_f32_16x16x32_bf16 v[10:13], v[154:157], v[202:205], v[10:13]
	v_mfma_f32_16x16x32_bf16 v[54:57], v[158:161], v[174:177], v[54:57]
	v_mfma_f32_16x16x32_bf16 v[50:53], v[166:169], v[174:177], v[50:53]
	v_mfma_f32_16x16x32_bf16 v[38:41], v[158:161], v[182:185], v[38:41]
	v_mfma_f32_16x16x32_bf16 v[34:37], v[166:169], v[182:185], v[34:37]
	v_mfma_f32_16x16x32_bf16 v[22:25], v[158:161], v[190:193], v[22:25]
	v_mfma_f32_16x16x32_bf16 v[18:21], v[166:169], v[190:193], v[18:21]
	v_mfma_f32_16x16x32_bf16 v[6:9], v[158:161], v[198:201], v[6:9]
	v_mfma_f32_16x16x32_bf16 v[2:5], v[166:169], v[198:201], v[2:5]
	v_mfma_f32_16x16x32_bf16 v[54:57], v[162:165], v[178:181], v[54:57]
	v_mfma_f32_16x16x32_bf16 v[50:53], v[170:173], v[178:181], v[50:53]
	v_mfma_f32_16x16x32_bf16 v[38:41], v[162:165], v[186:189], v[38:41]
	v_mfma_f32_16x16x32_bf16 v[34:37], v[170:173], v[186:189], v[34:37]
	v_mfma_f32_16x16x32_bf16 v[22:25], v[162:165], v[194:197], v[22:25]
	v_mfma_f32_16x16x32_bf16 v[18:21], v[170:173], v[194:197], v[18:21]
	v_mfma_f32_16x16x32_bf16 v[6:9], v[162:165], v[202:205], v[6:9]
	v_mfma_f32_16x16x32_bf16 v[2:5], v[170:173], v[202:205], v[2:5]
	s_barrier
	s_add_i32 s84, 0, 0x18000
	v_add_u32_e32 v0, s84, v144
	s_add_i32 s86, 0, 0x1c000
	ds_read_b128 v[136:139], v0
	ds_read_b128 v[146:149], v0 offset:1024
	ds_read_b128 v[150:153], v0 offset:2048
	ds_read_b128 v[154:157], v0 offset:3072
	v_add_u32_e32 v0, s86, v144
	ds_read_b128 v[158:161], v0
	ds_read_b128 v[162:165], v0 offset:1024
	ds_read_b128 v[166:169], v0 offset:2048
	ds_read_b128 v[170:173], v0 offset:3072
	s_add_i32 s83, s83, 0x100000
	ds_read_b128 v[174:177], v145 offset:32768
	ds_read_b128 v[178:181], v145 offset:33792
	ds_read_b128 v[182:185], v145 offset:34816
	ds_read_b128 v[186:189], v145 offset:35840
	ds_read_b128 v[190:193], v145 offset:36864
	ds_read_b128 v[194:197], v145 offset:37888
	ds_read_b128 v[198:201], v145 offset:38912
	ds_read_b128 v[202:205], v145 offset:39936
	s_mov_b32 m0, s24
	s_add_i32 vcc_lo, s83, 0x10000000
	s_add_u32 vcc_lo, s100, vcc_lo
	s_addc_u32 vcc_hi, s101, 0
	global_load_lds_dwordx4 v140, vcc
	s_mov_b32 m0, s25
	s_nop 0
	global_load_lds_dwordx4 v142, vcc
	s_waitcnt vmcnt(8)
	s_waitcnt lgkmcnt(0)
	s_barrier
	s_waitcnt lgkmcnt(0)
	v_mfma_f32_16x16x32_bf16 v[126:129], v[136:139], v[174:177], v[126:129]
	v_mfma_f32_16x16x32_bf16 v[122:125], v[150:153], v[174:177], v[122:125]
	v_mfma_f32_16x16x32_bf16 v[110:113], v[136:139], v[182:185], v[110:113]
	v_mfma_f32_16x16x32_bf16 v[106:109], v[150:153], v[182:185], v[106:109]
	v_mfma_f32_16x16x32_bf16 v[94:97], v[136:139], v[190:193], v[94:97]
	v_mfma_f32_16x16x32_bf16 v[90:93], v[150:153], v[190:193], v[90:93]
	v_mfma_f32_16x16x32_bf16 v[78:81], v[136:139], v[198:201], v[78:81]
	v_mfma_f32_16x16x32_bf16 v[74:77], v[150:153], v[198:201], v[74:77]
	v_mfma_f32_16x16x32_bf16 v[126:129], v[146:149], v[178:181], v[126:129]
	v_mfma_f32_16x16x32_bf16 v[122:125], v[154:157], v[178:181], v[122:125]
	v_mfma_f32_16x16x32_bf16 v[110:113], v[146:149], v[186:189], v[110:113]
	v_mfma_f32_16x16x32_bf16 v[106:109], v[154:157], v[186:189], v[106:109]
	v_mfma_f32_16x16x32_bf16 v[94:97], v[146:149], v[194:197], v[94:97]
	v_mfma_f32_16x16x32_bf16 v[90:93], v[154:157], v[194:197], v[90:93]
	v_mfma_f32_16x16x32_bf16 v[78:81], v[146:149], v[202:205], v[78:81]
	v_mfma_f32_16x16x32_bf16 v[74:77], v[154:157], v[202:205], v[74:77]
	v_mfma_f32_16x16x32_bf16 v[118:121], v[158:161], v[174:177], v[118:121]
	v_mfma_f32_16x16x32_bf16 v[114:117], v[166:169], v[174:177], v[114:117]
	v_mfma_f32_16x16x32_bf16 v[102:105], v[158:161], v[182:185], v[102:105]
	v_mfma_f32_16x16x32_bf16 v[98:101], v[166:169], v[182:185], v[98:101]
	v_mfma_f32_16x16x32_bf16 v[86:89], v[158:161], v[190:193], v[86:89]
	v_mfma_f32_16x16x32_bf16 v[82:85], v[166:169], v[190:193], v[82:85]
	v_mfma_f32_16x16x32_bf16 v[70:73], v[158:161], v[198:201], v[70:73]
	v_mfma_f32_16x16x32_bf16 v[66:69], v[166:169], v[198:201], v[66:69]
	v_mfma_f32_16x16x32_bf16 v[118:121], v[162:165], v[178:181], v[118:121]
	v_mfma_f32_16x16x32_bf16 v[114:117], v[170:173], v[178:181], v[114:117]
	v_mfma_f32_16x16x32_bf16 v[102:105], v[162:165], v[186:189], v[102:105]
	v_mfma_f32_16x16x32_bf16 v[98:101], v[170:173], v[186:189], v[98:101]
	v_mfma_f32_16x16x32_bf16 v[86:89], v[162:165], v[194:197], v[86:89]
	v_mfma_f32_16x16x32_bf16 v[82:85], v[170:173], v[194:197], v[82:85]
	v_mfma_f32_16x16x32_bf16 v[70:73], v[162:165], v[202:205], v[70:73]
	v_mfma_f32_16x16x32_bf16 v[66:69], v[170:173], v[202:205], v[66:69]
	s_barrier
; #define GAS __attribute__((address_space(1)))
; __device__ __forceinline__ unsigned cvt_pk_bf16(float lo, float hi) { const f32x2_t_ v = {lo, hi}; const bf16x2_t_ b = __builtin_convertvector(v, bf16x2_t_); return __builtin_bit_cast(unsigned, b); }
; #define PG8_STAGE(bufoff, gbase, voff) do { unsigned _g = (gbase); asm volatile("" : "+s"(_g));   _Pragma("unroll") for (int _i = 0; _i < 2; ++_i) \
;         __builtin_amdgcn_global_load_lds((const unsigned*)(wsb + (size_t)(unsigned)(_g + (voff)[_i])), (LAS unsigned*)(lds + (bufoff) + ldsw + _i * 8192), 16, 0, 0); } while (0)
; #define PG8_WAIT_V(n) asm volatile("s_waitcnt vmcnt(" #n ")" ::: "memory")
; #define PG8_WAIT_L(n) asm volatile("s_waitcnt lgkmcnt(" #n ")" ::: "memory")
; #define PG8_BAR __builtin_amdgcn_s_barrier()
; #define PG8_SCHED __builtin_amdgcn_sched_barrier(0)
;     ...
;             PG8_LDA(At, 1, 1); PG8_STAGE(PG8_SB(1, 0), b3, voffB); PG8_STAGE(PG8_SB(1, 1), b3 + hstep, voffB); PG8_STAGE(PG8_SA(1, 0), a3, voffA);
;             PG8_WAIT_V(8); PG8_WAIT_L(0); PG8_BAR; PG8_MMA(1, 0, At, B0); PG8_MMA(1, 1, At, B1); PG8_BAR; PG8_SCHED;
;     __device__ __forceinline__ void operator()(const f32x4 (&acc)[2][2][4][2], const pg8::GUnit& u, int wr, int wc, int fr, int fq) const {
;         const int row0 = u.pm * 256 + wr * 64 + fr, col0 = u.pn * 256 + wc * 32 + 8 * fq;
; #pragma unroll
;         for (int ai = 0; ai < 2; ++ai)
; #pragma unroll
;             for (int m = 0; m < 4; ++m) { const size_t row = (size_t)(row0 + ai * 128 + m * 16); float s = 0.f;
; #pragma unroll
;                 for (int bj = 0; bj < 2; ++bj) { const f32x4 v0 = acc[ai][bj][m][0], v1 = acc[ai][bj][m][1];
;                     s += (v0[0] * v0[0] + v0[1] * v0[1]) + (v0[2] * v0[2] + v0[3] * v0[3]) + (v1[0] * v1[0] + v1[1] * v1[1]) + (v1[2] * v1[2] + v1[3] * v1[3]);
;                     u32x4 w; w.x = cvt_pk_bf16(v0[0], v0[1]); w.y = cvt_pk_bf16(v0[2], v0[3]); w.z = cvt_pk_bf16(v1[0], v1[1]); w.w = cvt_pk_bf16(v1[2], v1[3]);
;                     *(GAS u32x4*)((GAS bf16_t*)O + row * DM + col0 + bj * 128) = w; }
;                 { const int ln = fr + 16 * fq; s += __int_as_float(__builtin_amdgcn_ds_bpermute((ln ^ 16) << 2, __float_as_int(s))); s += __int_as_float(__builtin_amdgcn_ds_bpermute((ln ^ 32) << 2, __float_as_int(s))); }
;                 if (fq == 0) ((GAS float*)RSQ)[row * 64 + u.pn * 4 + wc] = s; }
	s_add_i32 s83, s82, 0x80
	ds_read_b128 v[174:177], v145 offset:49152
	ds_read_b128 v[178:181], v145 offset:50176
	ds_read_b128 v[182:185], v145 offset:51200
	ds_read_b128 v[186:189], v145 offset:52224
	ds_read_b128 v[190:193], v145 offset:53248
	ds_read_b128 v[194:197], v145 offset:54272
	ds_read_b128 v[198:201], v145 offset:55296
	ds_read_b128 v[202:205], v145 offset:56320
	s_add_i32 s84, s84, s7
	s_add_i32 vcc_lo, s83, 0x10000000
	s_add_u32 vcc_lo, s100, vcc_lo
	s_addc_u32 vcc_hi, s101, 0
	s_mov_b32 m0, s84
	s_nop 0
	global_load_lds_dwordx4 v141, vcc
	s_add_i32 m0, s84, 0x2000
	s_add_i32 s82, s82, 0x100080
	global_load_lds_dwordx4 v143, vcc
	s_add_i32 s83, s86, s7
	s_add_i32 vcc_lo, s82, 0x10000000
	s_add_u32 vcc_lo, s100, vcc_lo
	s_addc_u32 vcc_hi, s101, 0
	s_mov_b32 m0, s83
	s_nop 0
	global_load_lds_dwordx4 v141, vcc
	s_add_i32 m0, s83, 0x2000
	s_nop 0
	global_load_lds_dwordx4 v143, vcc
	s_mov_b32 m0, s36
	s_add_i32 vcc_lo, s47, 0x10000000
	s_add_u32 vcc_lo, s100, vcc_lo
	s_addc_u32 vcc_hi, s101, 0
	global_load_lds_dwordx4 v140, vcc
	s_mov_b32 m0, s37
	s_nop 0
	global_load_lds_dwordx4 v142, vcc
	s_waitcnt vmcnt(8)
	s_waitcnt lgkmcnt(0)
	s_barrier
	s_waitcnt lgkmcnt(0)
	v_mfma_f32_16x16x32_bf16 v[62:65], v[136:139], v[174:177], v[62:65]
	v_mfma_f32_16x16x32_bf16 v[58:61], v[150:153], v[174:177], v[58:61]
	v_mfma_f32_16x16x32_bf16 v[46:49], v[136:139], v[182:185], v[46:49]
	v_mfma_f32_16x16x32_bf16 v[42:45], v[150:153], v[182:185], v[42:45]
	v_mfma_f32_16x16x32_bf16 v[30:33], v[136:139], v[190:193], v[30:33]
	v_mfma_f32_16x16x32_bf16 v[26:29], v[150:153], v[190:193], v[26:29]
	v_mfma_f32_16x16x32_bf16 v[14:17], v[136:139], v[198:201], v[14:17]
	v_mfma_f32_16x16x32_bf16 v[10:13], v[150:153], v[198:201], v[10:13]
	v_mfma_f32_16x16x32_bf16 v[62:65], v[146:149], v[178:181], v[62:65]
	v_mfma_f32_16x16x32_bf16 v[58:61], v[154:157], v[178:181], v[58:61]
	v_mfma_f32_16x16x32_bf16 v[46:49], v[146:149], v[186:189], v[46:49]
	v_mfma_f32_16x16x32_bf16 v[42:45], v[154:157], v[186:189], v[42:45]
	v_mfma_f32_16x16x32_bf16 v[30:33], v[146:149], v[194:197], v[30:33]
	v_mfma_f32_16x16x32_bf16 v[26:29], v[154:157], v[194:197], v[26:29]
	v_mfma_f32_16x16x32_bf16 v[14:17], v[146:149], v[202:205], v[14:17]
	v_mfma_f32_16x16x32_bf16 v[10:13], v[154:157], v[202:205], v[10:13]
	v_mfma_f32_16x16x32_bf16 v[54:57], v[158:161], v[174:177], v[54:57]
	v_mfma_f32_16x16x32_bf16 v[50:53], v[166:169], v[174:177], v[50:53]
	v_mfma_f32_16x16x32_bf16 v[38:41], v[158:161], v[182:185], v[38:41]
	v_mfma_f32_16x16x32_bf16 v[34:37], v[166:169], v[182:185], v[34:37]
	v_mfma_f32_16x16x32_bf16 v[22:25], v[158:161], v[190:193], v[22:25]
	v_mfma_f32_16x16x32_bf16 v[18:21], v[166:169], v[190:193], v[18:21]
	v_mfma_f32_16x16x32_bf16 v[6:9], v[158:161], v[198:201], v[6:9]
	v_mfma_f32_16x16x32_bf16 v[2:5], v[166:169], v[198:201], v[2:5]
	v_mfma_f32_16x16x32_bf16 v[54:57], v[162:165], v[178:181], v[54:57]
	v_mfma_f32_16x16x32_bf16 v[50:53], v[170:173], v[178:181], v[50:53]
	v_mfma_f32_16x16x32_bf16 v[38:41], v[162:165], v[186:189], v[38:41]
	v_mfma_f32_16x16x32_bf16 v[34:37], v[170:173], v[186:189], v[34:37]
	v_mfma_f32_16x16x32_bf16 v[22:25], v[162:165], v[194:197], v[22:25]
	v_mfma_f32_16x16x32_bf16 v[18:21], v[170:173], v[194:197], v[18:21]
	v_mfma_f32_16x16x32_bf16 v[6:9], v[162:165], v[202:205], v[6:9]
	v_mfma_f32_16x16x32_bf16 v[2:5], v[170:173], v[202:205], v[2:5]
	s_add_i32 s18, s18, 2
	s_addk_i32 s10, 0x100
	s_addk_i32 s11, 0x100
	s_cmp_gt_u32 s18, 61
	s_barrier
	s_cbranch_scc0 .LBB0_862
	s_setprio 0
	s_lshl_b32 s9, s9, 8
	v_mbcnt_lo_u32_b32 v139, -1, 0
	v_mbcnt_hi_u32_b32 v139, -1, v139
	s_add_i32 s9, s9, s3
	v_and_b32_e32 v0, 15, v139
	v_ashrrev_i32_e32 v146, 4, v139
	v_or_b32_e32 v138, s9, v0
	s_lshl_b32 s9, s8, 8
	s_or_b32 s9, s9, s88
	v_lshlrev_b32_e32 v147, 6, v146
	v_lshlrev_b32_e32 v0, 2, v0
	v_lshl_add_u32 v136, v146, 3, s9
	v_bitop3_b32 v146, v147, 64, v0 bitop3:0x36
	v_bitop3_b32 v0, v147, s92, v0 bitop3:0x36
	v_mul_f32_e32 v147, v127, v127
	v_mul_f32_e32 v150, v129, v129
	v_fmac_f32_e32 v147, v126, v126
	v_fmac_f32_e32 v150, v128, v128
	v_add_f32_e32 v147, v147, v150
	v_mul_f32_e32 v150, v123, v123
	v_fmac_f32_e32 v150, v122, v122
	v_cvt_pk_bf16_f32 v126, v126, v127
	v_cvt_pk_bf16_f32 v127, v128, v129
	v_cvt_pk_bf16_f32 v128, v122, v123
	v_mul_f32_e32 v122, v119, v119
	v_mul_f32_e32 v123, v121, v121
	v_fmac_f32_e32 v122, v118, v118
	v_fmac_f32_e32 v123, v120, v120
	v_add_f32_e32 v122, v122, v123
	v_mul_f32_e32 v123, v115, v115
	v_fmac_f32_e32 v123, v114, v114
	v_add_f32_e32 v147, v147, v150
	v_mul_f32_e32 v150, v125, v125
	v_add_f32_e32 v122, v122, v123
	v_mul_f32_e32 v123, v117, v117
	v_fmac_f32_e32 v150, v124, v124
	v_fmac_f32_e32 v123, v116, v116
	v_add_f32_e32 v147, v150, v147
	v_add_f32_e32 v122, v123, v122
	v_cvt_pk_bf16_f32 v129, v124, v125
	v_add_f32_e32 v124, v147, v122
	ds_bpermute_b32 v125, v146, v124
	v_cmp_gt_u32_e32 vcc, 16, v139
	v_ashrrev_i32_e32 v139, 31, v138
	v_lshlrev_b64 v[148:149], 13, v[138:139]
	v_ashrrev_i32_e32 v137, 31, v136
	v_lshl_add_u64 v[122:123], v[132:133], 0, v[148:149]
	v_lshl_add_u64 v[148:149], v[136:137], 1, v[122:123]
	v_cvt_pk_bf16_f32 v122, v118, v119
	s_waitcnt lgkmcnt(0)
	v_add_f32_e32 v118, v124, v125
	ds_bpermute_b32 v119, v0, v118
	s_lshl_b32 s8, s8, 2
	s_ashr_i32 s9, s8, 31
	v_cvt_pk_bf16_f32 v123, v120, v121
	v_cvt_pk_bf16_f32 v124, v114, v115
	v_cvt_pk_bf16_f32 v125, v116, v117
	global_store_dwordx4 v[148:149], v[126:129], off
	global_store_dwordx4 v[148:149], v[122:125], off offset:256
	s_and_saveexec_b64 s[10:11], vcc
	s_cbranch_execz .LBB0_865
	v_lshlrev_b64 v[114:115], 8, v[138:139]
	v_lshl_add_u64 v[114:115], v[134:135], 0, v[114:115]
	v_lshl_add_u64 v[114:115], s[8:9], 2, v[114:115]
	s_lshl_b32 s18, s43, 2
	s_waitcnt lgkmcnt(0)
	v_add_f32_e32 v116, v118, v119
	v_lshl_add_u64 v[114:115], v[114:115], 0, s[18:19]
	global_store_dword v[114:115], v116, off
